# plus: per-XCD NSA task queues, NSA tail/scan/adaLN-GEMV loads issued ahead with counted vmcnt, running max folded into QK accumulator init in the selected-block stream
# speedup vs baseline: 1.0351x; 1.0116x over previous
; #define LAS __attribute__((address_space(3)))
; __device__ __forceinline__ void phase0(Ctx& C, int mask) {
;     ...
; #pragma unroll 8
;                 for (int k4 = 0; k4 < 16; ++k4) { const int kl = 64 * kh + 4 * k4; float wv[4];
; #pragma unroll
;                     for (int q = 0; q < 4; ++q) wv[q] = __builtin_nontemporal_load(w_ada + (size_t)(128 * C.wave + kl + q) * 6144 + col);
; #pragma unroll
;                     for (int r = 0; r < 17; ++r) { const f4 s4 = *(const LAS f4*)(sil + r * 128 + kl); acc[r] += (s4[0] * wv[0] + s4[1] * wv[1]) + (s4[2] * wv[2] + s4[3] * wv[3]); } }
.LBB0_154:
	v_lshl_add_u64 v[84:85], v[78:79], 0, s[6:7]
	s_mov_b64 s[98:99], 0x6000
	v_mov_b64_e32 v[200:201], v[84:85]
	global_load_dword v136, v[200:201], off nt
	v_lshl_add_u64 v[200:201], v[200:201], 0, s[98:99]
	global_load_dword v138, v[200:201], off nt
	v_lshl_add_u64 v[200:201], v[200:201], 0, s[98:99]
	global_load_dword v139, v[200:201], off nt
	v_lshl_add_u64 v[200:201], v[200:201], 0, s[98:99]
	global_load_dword v137, v[200:201], off nt
	v_lshl_add_u64 v[200:201], v[200:201], 0, s[98:99]
	global_load_dword v140, v[200:201], off nt
	v_lshl_add_u64 v[200:201], v[200:201], 0, s[98:99]
	global_load_dword v142, v[200:201], off nt
	v_lshl_add_u64 v[200:201], v[200:201], 0, s[98:99]
	global_load_dword v143, v[200:201], off nt
	v_lshl_add_u64 v[200:201], v[200:201], 0, s[98:99]
	global_load_dword v141, v[200:201], off nt
	v_lshl_add_u64 v[200:201], v[200:201], 0, s[98:99]
	global_load_dword v144, v[200:201], off nt
	v_lshl_add_u64 v[200:201], v[200:201], 0, s[98:99]
	global_load_dword v146, v[200:201], off nt
	v_lshl_add_u64 v[200:201], v[200:201], 0, s[98:99]
	global_load_dword v147, v[200:201], off nt
	v_lshl_add_u64 v[200:201], v[200:201], 0, s[98:99]
	global_load_dword v145, v[200:201], off nt
	v_lshl_add_u64 v[200:201], v[200:201], 0, s[98:99]
	global_load_dword v148, v[200:201], off nt
	v_lshl_add_u64 v[200:201], v[200:201], 0, s[98:99]
	global_load_dword v150, v[200:201], off nt
	v_lshl_add_u64 v[200:201], v[200:201], 0, s[98:99]
	global_load_dword v151, v[200:201], off nt
	v_lshl_add_u64 v[200:201], v[200:201], 0, s[98:99]
	global_load_dword v149, v[200:201], off nt
	v_lshl_add_u64 v[200:201], v[200:201], 0, s[98:99]
	global_load_dword v152, v[200:201], off nt
	v_lshl_add_u64 v[200:201], v[200:201], 0, s[98:99]
	global_load_dword v154, v[200:201], off nt
	v_lshl_add_u64 v[200:201], v[200:201], 0, s[98:99]
	global_load_dword v155, v[200:201], off nt
	v_lshl_add_u64 v[200:201], v[200:201], 0, s[98:99]
	global_load_dword v153, v[200:201], off nt
	v_lshl_add_u64 v[200:201], v[200:201], 0, s[98:99]
	global_load_dword v156, v[200:201], off nt
	v_lshl_add_u64 v[200:201], v[200:201], 0, s[98:99]
	global_load_dword v158, v[200:201], off nt
	v_lshl_add_u64 v[200:201], v[200:201], 0, s[98:99]
	global_load_dword v159, v[200:201], off nt
	v_lshl_add_u64 v[200:201], v[200:201], 0, s[98:99]
	global_load_dword v157, v[200:201], off nt
	v_lshl_add_u64 v[200:201], v[200:201], 0, s[98:99]
	global_load_dword v160, v[200:201], off nt
	v_lshl_add_u64 v[200:201], v[200:201], 0, s[98:99]
	global_load_dword v162, v[200:201], off nt
	v_lshl_add_u64 v[200:201], v[200:201], 0, s[98:99]
	global_load_dword v163, v[200:201], off nt
	v_lshl_add_u64 v[200:201], v[200:201], 0, s[98:99]
	global_load_dword v161, v[200:201], off nt
	v_lshl_add_u64 v[200:201], v[200:201], 0, s[98:99]
	global_load_dword v164, v[200:201], off nt
	v_lshl_add_u64 v[200:201], v[200:201], 0, s[98:99]
	global_load_dword v166, v[200:201], off nt
	v_lshl_add_u64 v[200:201], v[200:201], 0, s[98:99]
	global_load_dword v167, v[200:201], off nt
	v_lshl_add_u64 v[200:201], v[200:201], 0, s[98:99]
	global_load_dword v165, v[200:201], off nt
	v_add_co_u32_e32 v0, vcc, s61, v84
	s_mov_b32 s0, 0xc000
	s_nop 0
	v_addc_co_u32_e32 v1, vcc, 0, v85, vcc
	v_add_co_u32_e32 v0, vcc, s0, v84
	s_mov_b32 s0, 0x12000
	s_nop 0
	v_addc_co_u32_e32 v1, vcc, 0, v85, vcc
	v_add_co_u32_e32 v0, vcc, s0, v84
	s_mov_b32 s0, 0x18000
	s_nop 0
	v_addc_co_u32_e32 v1, vcc, 0, v85, vcc
	ds_read_b128 v[16:19], v70
	ds_read_b128 v[8:11], v70 offset:16
	ds_read_b128 v[4:7], v70 offset:32
	ds_read_b128 v[0:3], v70 offset:48
	ds_read_b128 v[22:25], v70 offset:512
	ds_read_b128 v[32:35], v70 offset:1024
	ds_read_b128 v[38:41], v70 offset:1536
	ds_read_b128 v[46:49], v70 offset:2048
	ds_read_b128 v[58:61], v70 offset:2560
	ds_read_b128 v[62:65], v70 offset:3072
	ds_read_b128 v[86:89], v70 offset:3584
	ds_read_b128 v[90:93], v70 offset:4096
	ds_read_b128 v[94:97], v70 offset:4608
	ds_read_b128 v[98:101], v70 offset:5120
	ds_read_b128 v[102:105], v70 offset:5632
	ds_read_b128 v[106:109], v70 offset:6144
	ds_read_b128 v[118:121], v70 offset:6656
	ds_read_b128 v[122:125], v70 offset:7168
	ds_read_b128 v[126:129], v70 offset:7680
	ds_read_b128 v[130:133], v70 offset:8192
	s_waitcnt lgkmcnt(0)
	v_pk_mov_b32 v[26:27], v[16:17], v[22:23] op_sel:[1,0]
	v_mov_b32_e32 v17, v23
	v_pk_mov_b32 v[22:23], v[18:19], v[24:25] op_sel:[1,0]
	v_mov_b32_e32 v19, v25
	s_add_u32 s6, s6, 0xc0000
	s_addc_u32 s7, s7, 0
	s_cmp_eq_u32 s6, 0x180000
	s_waitcnt vmcnt(28)
; #define LAS __attribute__((address_space(3)))
; __device__ __forceinline__ void phase0(Ctx& C, int mask) {
;     ...
; #pragma unroll 8
;                 for (int k4 = 0; k4 < 16; ++k4) { const int kl = 64 * kh + 4 * k4; float wv[4];
; #pragma unroll
;                     for (int q = 0; q < 4; ++q) wv[q] = __builtin_nontemporal_load(w_ada + (size_t)(128 * C.wave + kl + q) * 6144 + col);
; #pragma unroll
;                     for (int r = 0; r < 17; ++r) { const f4 s4 = *(const LAS f4*)(sil + r * 128 + kl); acc[r] += (s4[0] * wv[0] + s4[1] * wv[1]) + (s4[2] * wv[2] + s4[3] * wv[3]); } }
	v_mov_b32_e32 v67, v136
	v_mov_b32_e32 v66, v138
	v_pk_mul_f32 v[16:17], v[66:67], v[16:17] op_sel:[1,0] op_sel_hi:[0,1]
	v_pk_fma_f32 v[16:17], v[66:67], v[26:27], v[16:17]
	v_mov_b32_e32 v55, v139
	v_mov_b32_e32 v54, v137
	v_pk_mul_f32 v[18:19], v[54:55], v[18:19] op_sel:[1,0] op_sel_hi:[0,1]
	v_pk_fma_f32 v[18:19], v[54:55], v[22:23], v[18:19]
	s_nop 0
	v_pk_add_f32 v[16:17], v[16:17], v[18:19]
	v_pk_mov_b32 v[18:19], v[32:33], v[38:39] op_sel:[1,0]
	v_mov_b32_e32 v33, v39
	v_pk_mul_f32 v[22:23], v[66:67], v[32:33] op_sel:[1,0] op_sel_hi:[0,1]
	v_pk_fma_f32 v[18:19], v[66:67], v[18:19], v[22:23]
	v_pk_mov_b32 v[22:23], v[34:35], v[40:41] op_sel:[1,0]
	v_mov_b32_e32 v35, v41
	v_pk_mul_f32 v[24:25], v[54:55], v[34:35] op_sel:[1,0] op_sel_hi:[0,1]
	v_pk_fma_f32 v[22:23], v[54:55], v[22:23], v[24:25]
	v_pk_add_f32 v[16:17], v[56:57], v[16:17]
	v_pk_add_f32 v[18:19], v[18:19], v[22:23]
	v_pk_mov_b32 v[22:23], v[46:47], v[58:59] op_sel:[1,0]
	v_mov_b32_e32 v47, v59
	v_pk_mul_f32 v[24:25], v[66:67], v[46:47] op_sel:[1,0] op_sel_hi:[0,1]
	v_pk_fma_f32 v[22:23], v[66:67], v[22:23], v[24:25]
	v_pk_mov_b32 v[24:25], v[48:49], v[60:61] op_sel:[1,0]
	v_mov_b32_e32 v49, v61
	v_pk_mul_f32 v[26:27], v[54:55], v[48:49] op_sel:[1,0] op_sel_hi:[0,1]
	v_pk_fma_f32 v[24:25], v[54:55], v[24:25], v[26:27]
	v_pk_add_f32 v[18:19], v[52:53], v[18:19]
	v_pk_add_f32 v[22:23], v[22:23], v[24:25]
	v_pk_mov_b32 v[24:25], v[62:63], v[86:87] op_sel:[1,0]
	v_mov_b32_e32 v63, v87
	v_pk_mul_f32 v[26:27], v[66:67], v[62:63] op_sel:[1,0] op_sel_hi:[0,1]
	v_pk_fma_f32 v[24:25], v[66:67], v[24:25], v[26:27]
	v_pk_mov_b32 v[26:27], v[64:65], v[88:89] op_sel:[1,0]
	v_mov_b32_e32 v65, v89
	v_pk_mul_f32 v[32:33], v[54:55], v[64:65] op_sel:[1,0] op_sel_hi:[0,1]
	v_pk_fma_f32 v[26:27], v[54:55], v[26:27], v[32:33]
	v_pk_add_f32 v[22:23], v[44:45], v[22:23]
	v_pk_add_f32 v[24:25], v[24:25], v[26:27]
	v_pk_mov_b32 v[26:27], v[90:91], v[94:95] op_sel:[1,0]
	v_mov_b32_e32 v91, v95
	v_pk_mul_f32 v[32:33], v[66:67], v[90:91] op_sel:[1,0] op_sel_hi:[0,1]
	v_pk_fma_f32 v[26:27], v[66:67], v[26:27], v[32:33]
	v_pk_mov_b32 v[32:33], v[92:93], v[96:97] op_sel:[1,0]
	v_mov_b32_e32 v93, v97
	v_pk_mul_f32 v[34:35], v[54:55], v[92:93] op_sel:[1,0] op_sel_hi:[0,1]
	v_pk_fma_f32 v[32:33], v[54:55], v[32:33], v[34:35]
	v_pk_add_f32 v[24:25], v[36:37], v[24:25]
	v_pk_add_f32 v[26:27], v[26:27], v[32:33]
	s_nop 0
	v_pk_add_f32 v[26:27], v[28:29], v[26:27]
	v_pk_mov_b32 v[28:29], v[98:99], v[102:103] op_sel:[1,0]
	v_mov_b32_e32 v99, v103
	v_pk_mul_f32 v[32:33], v[66:67], v[98:99] op_sel:[1,0] op_sel_hi:[0,1]
	v_pk_fma_f32 v[28:29], v[66:67], v[28:29], v[32:33]
	v_pk_mov_b32 v[32:33], v[100:101], v[104:105] op_sel:[1,0]
	v_mov_b32_e32 v101, v105
	v_pk_mul_f32 v[34:35], v[54:55], v[100:101] op_sel:[1,0] op_sel_hi:[0,1]
	v_pk_fma_f32 v[32:33], v[54:55], v[32:33], v[34:35]
	s_nop 0
	v_pk_add_f32 v[28:29], v[28:29], v[32:33]
	s_nop 0
	v_pk_add_f32 v[20:21], v[20:21], v[28:29]
	v_pk_mov_b32 v[28:29], v[106:107], v[118:119] op_sel:[1,0]
	v_mov_b32_e32 v107, v119
	v_pk_mul_f32 v[32:33], v[66:67], v[106:107] op_sel:[1,0] op_sel_hi:[0,1]
	v_pk_fma_f32 v[28:29], v[66:67], v[28:29], v[32:33]
	v_pk_mov_b32 v[32:33], v[108:109], v[120:121] op_sel:[1,0]
	v_mov_b32_e32 v109, v121
	v_pk_mul_f32 v[34:35], v[54:55], v[108:109] op_sel:[1,0] op_sel_hi:[0,1]
	v_pk_fma_f32 v[32:33], v[54:55], v[32:33], v[34:35]
	s_nop 0
	v_pk_add_f32 v[28:29], v[28:29], v[32:33]
	s_nop 0
	v_pk_add_f32 v[12:13], v[12:13], v[28:29]
	v_pk_mov_b32 v[28:29], v[122:123], v[126:127] op_sel:[1,0]
	v_mov_b32_e32 v123, v127
	v_pk_mul_f32 v[32:33], v[66:67], v[122:123] op_sel:[1,0] op_sel_hi:[0,1]
	v_pk_fma_f32 v[28:29], v[66:67], v[28:29], v[32:33]
	v_pk_mov_b32 v[32:33], v[124:125], v[128:129] op_sel:[1,0]
	v_mov_b32_e32 v125, v129
	v_pk_mul_f32 v[34:35], v[54:55], v[124:125] op_sel:[1,0] op_sel_hi:[0,1]
	v_pk_fma_f32 v[32:33], v[54:55], v[32:33], v[34:35]
	s_nop 0
	v_pk_add_f32 v[28:29], v[28:29], v[32:33]
	s_nop 0
	v_pk_add_f32 v[14:15], v[14:15], v[28:29]
	v_mov_b32_e32 v28, v131
	v_mov_b32_e32 v131, v133
	v_mov_b32_e32 v29, v132
	v_pk_mul_f32 v[32:33], v[136:137], v[130:131]
	s_nop 0
	v_pk_fma_f32 v[28:29], v[138:139], v[28:29], v[32:33]
	s_nop 0
	v_add_f32_e32 v28, v28, v29
	v_add_f32_e32 v32, v30, v28
	v_add_co_u32_e32 v28, vcc, s0, v84
	s_mov_b32 s0, 0x1e000
	s_nop 0
	v_addc_co_u32_e32 v29, vcc, 0, v85, vcc
	v_add_co_u32_e32 v30, vcc, s0, v84
	s_mov_b32 s0, 0x24000
	s_nop 0
	v_addc_co_u32_e32 v31, vcc, 0, v85, vcc
	v_add_co_u32_e32 v34, vcc, s0, v84
	s_mov_b32 s0, 0x2a000
	s_nop 0
	v_addc_co_u32_e32 v35, vcc, 0, v85, vcc
	s_nop 0
	s_waitcnt vmcnt(26) lgkmcnt(0)
	v_mov_b32_e32 v135, v140
	v_add_co_u32_e32 v34, vcc, s0, v84
	v_mov_b32_e32 v134, v142
	s_nop 0
	v_addc_co_u32_e32 v35, vcc, 0, v85, vcc
	ds_read_b128 v[34:37], v70 offset:528
	ds_read_b128 v[38:41], v70 offset:1040
	ds_read_b128 v[42:45], v70 offset:1552
	ds_read_b128 v[46:49], v70 offset:2064
	ds_read_b128 v[50:53], v70 offset:2576
	ds_read_b128 v[62:65], v70 offset:3088
	ds_read_b128 v[86:89], v70 offset:3600
	ds_read_b128 v[90:93], v70 offset:4112
	ds_read_b128 v[94:97], v70 offset:4624
	ds_read_b128 v[98:101], v70 offset:5136
	ds_read_b128 v[102:105], v70 offset:5648
	ds_read_b128 v[106:109], v70 offset:6160
	ds_read_b128 v[118:121], v70 offset:6672
	ds_read_b128 v[122:125], v70 offset:7184
	ds_read_b128 v[126:129], v70 offset:7696
	ds_read_b128 v[130:133], v70 offset:8208
	s_waitcnt lgkmcnt(0)
	v_pk_mov_b32 v[56:57], v[8:9], v[34:35] op_sel:[1,0]
	v_mov_b32_e32 v9, v35
	v_pk_mov_b32 v[34:35], v[10:11], v[36:37] op_sel:[1,0]
	v_mov_b32_e32 v11, v37
	v_pk_mul_f32 v[8:9], v[134:135], v[8:9] op_sel:[1,0] op_sel_hi:[0,1]
	v_pk_fma_f32 v[8:9], v[134:135], v[56:57], v[8:9]
	s_mov_b32 s0, 0x30000
	s_waitcnt vmcnt(24)
; #define LAS __attribute__((address_space(3)))
; __device__ __forceinline__ void phase0(Ctx& C, int mask) {
;     ...
; #pragma unroll 8
;                 for (int k4 = 0; k4 < 16; ++k4) { const int kl = 64 * kh + 4 * k4; float wv[4];
; #pragma unroll
;                     for (int q = 0; q < 4; ++q) wv[q] = __builtin_nontemporal_load(w_ada + (size_t)(128 * C.wave + kl + q) * 6144 + col);
; #pragma unroll
;                     for (int r = 0; r < 17; ++r) { const f4 s4 = *(const LAS f4*)(sil + r * 128 + kl); acc[r] += (s4[0] * wv[0] + s4[1] * wv[1]) + (s4[2] * wv[2] + s4[3] * wv[3]); } }
	v_mov_b32_e32 v55, v143
	v_mov_b32_e32 v54, v141
	v_pk_mul_f32 v[10:11], v[54:55], v[10:11] op_sel:[1,0] op_sel_hi:[0,1]
	v_pk_fma_f32 v[10:11], v[54:55], v[34:35], v[10:11]
	s_nop 0
	v_pk_add_f32 v[8:9], v[8:9], v[10:11]
	s_nop 0
	v_pk_add_f32 v[56:57], v[16:17], v[8:9]
	v_pk_mov_b32 v[8:9], v[38:39], v[42:43] op_sel:[1,0]
	v_mov_b32_e32 v39, v43
	v_pk_mul_f32 v[10:11], v[134:135], v[38:39] op_sel:[1,0] op_sel_hi:[0,1]
	v_pk_fma_f32 v[8:9], v[134:135], v[8:9], v[10:11]
	v_pk_mov_b32 v[10:11], v[40:41], v[44:45] op_sel:[1,0]
	v_mov_b32_e32 v41, v45
	v_pk_mul_f32 v[16:17], v[54:55], v[40:41] op_sel:[1,0] op_sel_hi:[0,1]
	v_pk_fma_f32 v[10:11], v[54:55], v[10:11], v[16:17]
	s_nop 0
	v_pk_add_f32 v[8:9], v[8:9], v[10:11]
	s_nop 0
	v_pk_add_f32 v[58:59], v[18:19], v[8:9]
	v_pk_mov_b32 v[8:9], v[46:47], v[50:51] op_sel:[1,0]
	v_mov_b32_e32 v47, v51
	v_pk_mul_f32 v[10:11], v[134:135], v[46:47] op_sel:[1,0] op_sel_hi:[0,1]
	v_pk_fma_f32 v[8:9], v[134:135], v[8:9], v[10:11]
	v_pk_mov_b32 v[10:11], v[48:49], v[52:53] op_sel:[1,0]
	v_mov_b32_e32 v49, v53
	v_pk_mul_f32 v[16:17], v[54:55], v[48:49] op_sel:[1,0] op_sel_hi:[0,1]
	v_pk_fma_f32 v[10:11], v[54:55], v[10:11], v[16:17]
	s_nop 0
	v_pk_add_f32 v[8:9], v[8:9], v[10:11]
	s_nop 0
	v_pk_add_f32 v[60:61], v[22:23], v[8:9]
	v_pk_mov_b32 v[8:9], v[62:63], v[86:87] op_sel:[1,0]
	v_mov_b32_e32 v63, v87
	v_pk_mul_f32 v[10:11], v[134:135], v[62:63] op_sel:[1,0] op_sel_hi:[0,1]
	v_pk_fma_f32 v[8:9], v[134:135], v[8:9], v[10:11]
	v_pk_mov_b32 v[10:11], v[64:65], v[88:89] op_sel:[1,0]
	v_mov_b32_e32 v65, v89
	v_pk_mul_f32 v[16:17], v[54:55], v[64:65] op_sel:[1,0] op_sel_hi:[0,1]
	v_pk_fma_f32 v[10:11], v[54:55], v[10:11], v[16:17]
	s_nop 0
	v_pk_add_f32 v[8:9], v[8:9], v[10:11]
	s_nop 0
	v_pk_add_f32 v[62:63], v[24:25], v[8:9]
	v_pk_mov_b32 v[8:9], v[90:91], v[94:95] op_sel:[1,0]
	v_mov_b32_e32 v91, v95
	v_pk_mul_f32 v[10:11], v[134:135], v[90:91] op_sel:[1,0] op_sel_hi:[0,1]
	v_pk_fma_f32 v[8:9], v[134:135], v[8:9], v[10:11]
	v_pk_mov_b32 v[10:11], v[92:93], v[96:97] op_sel:[1,0]
	v_mov_b32_e32 v93, v97
	v_pk_mul_f32 v[16:17], v[54:55], v[92:93] op_sel:[1,0] op_sel_hi:[0,1]
	v_pk_fma_f32 v[10:11], v[54:55], v[10:11], v[16:17]
	s_nop 0
	v_pk_add_f32 v[8:9], v[8:9], v[10:11]
	s_nop 0
	v_pk_add_f32 v[64:65], v[26:27], v[8:9]
	v_pk_mov_b32 v[8:9], v[98:99], v[102:103] op_sel:[1,0]
	v_mov_b32_e32 v99, v103
	v_pk_mul_f32 v[10:11], v[134:135], v[98:99] op_sel:[1,0] op_sel_hi:[0,1]
	v_pk_fma_f32 v[8:9], v[134:135], v[8:9], v[10:11]
	v_pk_mov_b32 v[10:11], v[100:101], v[104:105] op_sel:[1,0]
	v_mov_b32_e32 v101, v105
	v_pk_mul_f32 v[16:17], v[54:55], v[100:101] op_sel:[1,0] op_sel_hi:[0,1]
	v_pk_fma_f32 v[10:11], v[54:55], v[10:11], v[16:17]
	s_nop 0
	v_pk_add_f32 v[8:9], v[8:9], v[10:11]
	s_nop 0
	v_pk_add_f32 v[66:67], v[20:21], v[8:9]
	v_pk_mov_b32 v[8:9], v[106:107], v[118:119] op_sel:[1,0]
	v_mov_b32_e32 v107, v119
	v_pk_mul_f32 v[10:11], v[134:135], v[106:107] op_sel:[1,0] op_sel_hi:[0,1]
	v_pk_fma_f32 v[8:9], v[134:135], v[8:9], v[10:11]
	v_pk_mov_b32 v[10:11], v[108:109], v[120:121] op_sel:[1,0]
	v_mov_b32_e32 v109, v121
	v_pk_mul_f32 v[16:17], v[54:55], v[108:109] op_sel:[1,0] op_sel_hi:[0,1]
	v_pk_fma_f32 v[10:11], v[54:55], v[10:11], v[16:17]
	s_nop 0
	v_pk_add_f32 v[8:9], v[8:9], v[10:11]
	s_nop 0
	v_pk_add_f32 v[86:87], v[12:13], v[8:9]
	v_pk_mov_b32 v[8:9], v[122:123], v[126:127] op_sel:[1,0]
	v_mov_b32_e32 v123, v127
	v_pk_mul_f32 v[10:11], v[134:135], v[122:123] op_sel:[1,0] op_sel_hi:[0,1]
	v_pk_fma_f32 v[8:9], v[134:135], v[8:9], v[10:11]
	v_pk_mov_b32 v[10:11], v[124:125], v[128:129] op_sel:[1,0]
	v_mov_b32_e32 v125, v129
	v_pk_mul_f32 v[12:13], v[54:55], v[124:125] op_sel:[1,0] op_sel_hi:[0,1]
	v_pk_fma_f32 v[10:11], v[54:55], v[10:11], v[12:13]
	s_nop 0
	v_pk_add_f32 v[8:9], v[8:9], v[10:11]
	s_nop 0
	v_pk_add_f32 v[88:89], v[14:15], v[8:9]
	v_mov_b32_e32 v8, v131
	v_mov_b32_e32 v131, v133
	v_mov_b32_e32 v9, v132
	v_pk_mul_f32 v[10:11], v[140:141], v[130:131]
	s_nop 0
	v_pk_fma_f32 v[8:9], v[142:143], v[8:9], v[10:11]
	s_nop 0
	v_add_f32_e32 v8, v8, v9
	v_add_f32_e32 v77, v32, v8
	v_add_co_u32_e32 v8, vcc, s0, v84
	s_mov_b32 s0, 0x36000
	s_nop 0
	v_addc_co_u32_e32 v9, vcc, 0, v85, vcc
	v_add_co_u32_e32 v8, vcc, s0, v84
	s_mov_b32 s0, 0x3c000
	s_nop 0
	v_addc_co_u32_e32 v9, vcc, 0, v85, vcc
	v_add_co_u32_e32 v8, vcc, s0, v84
	s_mov_b32 s0, 0x42000
	s_nop 0
	v_addc_co_u32_e32 v9, vcc, 0, v85, vcc
	v_add_co_u32_e32 v8, vcc, s0, v84
	s_mov_b32 s0, 0x48000
	s_nop 0
	v_addc_co_u32_e32 v9, vcc, 0, v85, vcc
	ds_read_b128 v[52:55], v70 offset:544
	ds_read_b128 v[44:47], v70 offset:1056
	ds_read_b128 v[48:51], v70 offset:1568
	ds_read_b128 v[36:39], v70 offset:2080
	ds_read_b128 v[40:43], v70 offset:2592
	ds_read_b128 v[28:31], v70 offset:3104
	ds_read_b128 v[32:35], v70 offset:3616
	ds_read_b128 v[20:23], v70 offset:4128
	ds_read_b128 v[24:27], v70 offset:4640
	ds_read_b128 v[12:15], v70 offset:5152
	ds_read_b128 v[16:19], v70 offset:5664
	ds_read_b128 v[8:11], v70 offset:6176
	ds_read_b128 v[118:121], v70 offset:6688
	ds_read_b128 v[122:125], v70 offset:7200
	ds_read_b128 v[126:129], v70 offset:7712
	ds_read_b128 v[130:133], v70 offset:8224
	s_waitcnt lgkmcnt(0)
	v_pk_mov_b32 v[92:93], v[4:5], v[52:53] op_sel:[1,0]
	v_mov_b32_e32 v5, v53
	v_pk_mov_b32 v[52:53], v[6:7], v[54:55] op_sel:[1,0]
	v_mov_b32_e32 v7, v55
	s_waitcnt vmcnt(20)
; #define LAS __attribute__((address_space(3)))
; __device__ __forceinline__ void phase0(Ctx& C, int mask) {
;     ...
; #pragma unroll 8
;                 for (int k4 = 0; k4 < 16; ++k4) { const int kl = 64 * kh + 4 * k4; float wv[4];
; #pragma unroll
;                     for (int q = 0; q < 4; ++q) wv[q] = __builtin_nontemporal_load(w_ada + (size_t)(128 * C.wave + kl + q) * 6144 + col);
; #pragma unroll
;                     for (int r = 0; r < 17; ++r) { const f4 s4 = *(const LAS f4*)(sil + r * 128 + kl); acc[r] += (s4[0] * wv[0] + s4[1] * wv[1]) + (s4[2] * wv[2] + s4[3] * wv[3]); } }
	v_mov_b32_e32 v135, v144
	v_mov_b32_e32 v134, v146
	v_pk_mul_f32 v[4:5], v[134:135], v[4:5] op_sel:[1,0] op_sel_hi:[0,1]
	v_pk_fma_f32 v[4:5], v[134:135], v[92:93], v[4:5]
	v_mov_b32_e32 v109, v147
	v_mov_b32_e32 v108, v145
	v_pk_mul_f32 v[6:7], v[108:109], v[6:7] op_sel:[1,0] op_sel_hi:[0,1]
	v_pk_fma_f32 v[6:7], v[108:109], v[52:53], v[6:7]
	s_nop 0
	v_pk_add_f32 v[4:5], v[4:5], v[6:7]
	s_nop 0
	v_pk_add_f32 v[104:105], v[56:57], v[4:5]
	v_pk_mov_b32 v[4:5], v[44:45], v[48:49] op_sel:[1,0]
	v_mov_b32_e32 v45, v49
	v_pk_mul_f32 v[6:7], v[134:135], v[44:45] op_sel:[1,0] op_sel_hi:[0,1]
	v_pk_fma_f32 v[4:5], v[134:135], v[4:5], v[6:7]
	v_pk_mov_b32 v[6:7], v[46:47], v[50:51] op_sel:[1,0]
	v_mov_b32_e32 v47, v51
	v_pk_mul_f32 v[44:45], v[108:109], v[46:47] op_sel:[1,0] op_sel_hi:[0,1]
	v_pk_fma_f32 v[6:7], v[108:109], v[6:7], v[44:45]
	s_nop 0
	v_pk_add_f32 v[4:5], v[4:5], v[6:7]
	s_nop 0
	v_pk_add_f32 v[102:103], v[58:59], v[4:5]
	v_pk_mov_b32 v[4:5], v[36:37], v[40:41] op_sel:[1,0]
	v_mov_b32_e32 v37, v41
	v_pk_mul_f32 v[6:7], v[134:135], v[36:37] op_sel:[1,0] op_sel_hi:[0,1]
	v_pk_fma_f32 v[4:5], v[134:135], v[4:5], v[6:7]
	v_pk_mov_b32 v[6:7], v[38:39], v[42:43] op_sel:[1,0]
	v_mov_b32_e32 v39, v43
	v_pk_mul_f32 v[36:37], v[108:109], v[38:39] op_sel:[1,0] op_sel_hi:[0,1]
	v_pk_fma_f32 v[6:7], v[108:109], v[6:7], v[36:37]
	s_nop 0
	v_pk_add_f32 v[4:5], v[4:5], v[6:7]
	s_nop 0
	v_pk_add_f32 v[100:101], v[60:61], v[4:5]
	v_pk_mov_b32 v[4:5], v[28:29], v[32:33] op_sel:[1,0]
	v_mov_b32_e32 v29, v33
	v_pk_mul_f32 v[6:7], v[134:135], v[28:29] op_sel:[1,0] op_sel_hi:[0,1]
	v_pk_fma_f32 v[4:5], v[134:135], v[4:5], v[6:7]
	v_pk_mov_b32 v[6:7], v[30:31], v[34:35] op_sel:[1,0]
	v_mov_b32_e32 v31, v35
	v_pk_mul_f32 v[28:29], v[108:109], v[30:31] op_sel:[1,0] op_sel_hi:[0,1]
	v_pk_fma_f32 v[6:7], v[108:109], v[6:7], v[28:29]
	s_nop 0
	v_pk_add_f32 v[4:5], v[4:5], v[6:7]
	s_nop 0
	v_pk_add_f32 v[98:99], v[62:63], v[4:5]
	v_pk_mov_b32 v[4:5], v[20:21], v[24:25] op_sel:[1,0]
	v_mov_b32_e32 v21, v25
	v_pk_mul_f32 v[6:7], v[134:135], v[20:21] op_sel:[1,0] op_sel_hi:[0,1]
	v_pk_fma_f32 v[4:5], v[134:135], v[4:5], v[6:7]
	v_pk_mov_b32 v[6:7], v[22:23], v[26:27] op_sel:[1,0]
	v_mov_b32_e32 v23, v27
	v_pk_mul_f32 v[20:21], v[108:109], v[22:23] op_sel:[1,0] op_sel_hi:[0,1]
	v_pk_fma_f32 v[6:7], v[108:109], v[6:7], v[20:21]
	s_nop 0
	v_pk_add_f32 v[4:5], v[4:5], v[6:7]
	s_nop 0
	v_pk_add_f32 v[96:97], v[64:65], v[4:5]
	v_pk_mov_b32 v[4:5], v[12:13], v[16:17] op_sel:[1,0]
	v_mov_b32_e32 v13, v17
	v_pk_mul_f32 v[6:7], v[134:135], v[12:13] op_sel:[1,0] op_sel_hi:[0,1]
	v_pk_fma_f32 v[4:5], v[134:135], v[4:5], v[6:7]
	v_pk_mov_b32 v[6:7], v[14:15], v[18:19] op_sel:[1,0]
	v_mov_b32_e32 v15, v19
	v_pk_mul_f32 v[12:13], v[108:109], v[14:15] op_sel:[1,0] op_sel_hi:[0,1]
	v_pk_fma_f32 v[6:7], v[108:109], v[6:7], v[12:13]
	s_nop 0
	v_pk_add_f32 v[4:5], v[4:5], v[6:7]
	s_nop 0
	v_pk_add_f32 v[94:95], v[66:67], v[4:5]
	v_pk_mov_b32 v[4:5], v[8:9], v[118:119] op_sel:[1,0]
	v_mov_b32_e32 v9, v119
	v_pk_mul_f32 v[6:7], v[134:135], v[8:9] op_sel:[1,0] op_sel_hi:[0,1]
	v_pk_fma_f32 v[4:5], v[134:135], v[4:5], v[6:7]
	v_pk_mov_b32 v[6:7], v[10:11], v[120:121] op_sel:[1,0]
	v_mov_b32_e32 v11, v121
	v_pk_mul_f32 v[8:9], v[108:109], v[10:11] op_sel:[1,0] op_sel_hi:[0,1]
	v_pk_fma_f32 v[6:7], v[108:109], v[6:7], v[8:9]
	s_nop 0
	v_pk_add_f32 v[4:5], v[4:5], v[6:7]
	s_nop 0
	v_pk_add_f32 v[92:93], v[86:87], v[4:5]
	v_pk_mov_b32 v[4:5], v[122:123], v[126:127] op_sel:[1,0]
	v_mov_b32_e32 v123, v127
	v_pk_mul_f32 v[6:7], v[134:135], v[122:123] op_sel:[1,0] op_sel_hi:[0,1]
	v_pk_fma_f32 v[4:5], v[134:135], v[4:5], v[6:7]
	v_pk_mov_b32 v[6:7], v[124:125], v[128:129] op_sel:[1,0]
	v_mov_b32_e32 v125, v129
	v_pk_mul_f32 v[8:9], v[108:109], v[124:125] op_sel:[1,0] op_sel_hi:[0,1]
	v_pk_fma_f32 v[6:7], v[108:109], v[6:7], v[8:9]
	s_nop 0
	v_pk_add_f32 v[4:5], v[4:5], v[6:7]
	s_nop 0
	v_pk_add_f32 v[86:87], v[88:89], v[4:5]
	v_mov_b32_e32 v4, v131
	v_mov_b32_e32 v131, v133
	v_mov_b32_e32 v5, v132
	v_pk_mul_f32 v[6:7], v[144:145], v[130:131]
	s_nop 0
	v_pk_fma_f32 v[4:5], v[146:147], v[4:5], v[6:7]
	s_nop 0
	v_add_f32_e32 v4, v4, v5
	v_add_f32_e32 v77, v77, v4
	v_add_co_u32_e32 v4, vcc, s0, v84
	s_mov_b32 s0, 0x4e000
	s_nop 0
	v_addc_co_u32_e32 v5, vcc, 0, v85, vcc
	v_add_co_u32_e32 v4, vcc, s0, v84
	s_mov_b32 s0, 0x54000
	s_nop 0
	v_addc_co_u32_e32 v5, vcc, 0, v85, vcc
	v_add_co_u32_e32 v4, vcc, s0, v84
	s_mov_b32 s0, 0x5a000
	s_nop 0
	v_addc_co_u32_e32 v5, vcc, 0, v85, vcc
	v_add_co_u32_e32 v4, vcc, s0, v84
	s_mov_b32 s0, 0x60000
	s_nop 0
	v_addc_co_u32_e32 v5, vcc, 0, v85, vcc
	ds_read_b128 v[64:67], v70 offset:560
	ds_read_b128 v[56:59], v70 offset:1072
	ds_read_b128 v[60:63], v70 offset:1584
	ds_read_b128 v[40:43], v70 offset:2096
	ds_read_b128 v[44:47], v70 offset:2608
	ds_read_b128 v[20:23], v70 offset:3120
	ds_read_b128 v[24:27], v70 offset:3632
	ds_read_b128 v[12:15], v70 offset:4144
	ds_read_b128 v[16:19], v70 offset:4656
	ds_read_b128 v[4:7], v70 offset:5168
	ds_read_b128 v[8:11], v70 offset:5680
	ds_read_b128 v[48:51], v70 offset:6192
	ds_read_b128 v[52:55], v70 offset:6704
	ds_read_b128 v[32:35], v70 offset:7216
	ds_read_b128 v[36:39], v70 offset:7728
	ds_read_b128 v[28:31], v70 offset:8240
	s_waitcnt lgkmcnt(0)
	v_pk_mov_b32 v[118:119], v[0:1], v[64:65] op_sel:[1,0]
	v_mov_b32_e32 v1, v65
	v_pk_mov_b32 v[64:65], v[2:3], v[66:67] op_sel:[1,0]
	v_mov_b32_e32 v3, v67
	s_waitcnt vmcnt(16)
; #define LAS __attribute__((address_space(3)))
; __device__ __forceinline__ void phase0(Ctx& C, int mask) {
;     ...
; #pragma unroll 8
;                 for (int k4 = 0; k4 < 16; ++k4) { const int kl = 64 * kh + 4 * k4; float wv[4];
; #pragma unroll
;                     for (int q = 0; q < 4; ++q) wv[q] = __builtin_nontemporal_load(w_ada + (size_t)(128 * C.wave + kl + q) * 6144 + col);
; #pragma unroll
;                     for (int r = 0; r < 17; ++r) { const f4 s4 = *(const LAS f4*)(sil + r * 128 + kl); acc[r] += (s4[0] * wv[0] + s4[1] * wv[1]) + (s4[2] * wv[2] + s4[3] * wv[3]); } }
	v_mov_b32_e32 v109, v148
	v_mov_b32_e32 v108, v150
	v_pk_mul_f32 v[0:1], v[108:109], v[0:1] op_sel:[1,0] op_sel_hi:[0,1]
	v_pk_fma_f32 v[0:1], v[108:109], v[118:119], v[0:1]
	v_mov_b32_e32 v107, v151
	v_mov_b32_e32 v106, v149
	v_pk_mul_f32 v[2:3], v[106:107], v[2:3] op_sel:[1,0] op_sel_hi:[0,1]
	v_pk_fma_f32 v[2:3], v[106:107], v[64:65], v[2:3]
	s_nop 0
	v_pk_add_f32 v[0:1], v[0:1], v[2:3]
	v_pk_mov_b32 v[2:3], v[56:57], v[60:61] op_sel:[1,0]
	v_mov_b32_e32 v57, v61
	v_pk_mul_f32 v[56:57], v[108:109], v[56:57] op_sel:[1,0] op_sel_hi:[0,1]
	v_pk_fma_f32 v[2:3], v[108:109], v[2:3], v[56:57]
	v_pk_mov_b32 v[56:57], v[58:59], v[62:63] op_sel:[1,0]
	v_mov_b32_e32 v59, v63
	v_pk_mul_f32 v[58:59], v[106:107], v[58:59] op_sel:[1,0] op_sel_hi:[0,1]
	v_pk_fma_f32 v[56:57], v[106:107], v[56:57], v[58:59]
	v_pk_add_f32 v[0:1], v[104:105], v[0:1]
	v_pk_add_f32 v[2:3], v[2:3], v[56:57]
	v_pk_mov_b32 v[56:57], v[40:41], v[44:45] op_sel:[1,0]
	v_mov_b32_e32 v41, v45
	v_pk_mov_b32 v[44:45], v[42:43], v[46:47] op_sel:[1,0]
	v_mov_b32_e32 v43, v47
	v_pk_mul_f32 v[40:41], v[108:109], v[40:41] op_sel:[1,0] op_sel_hi:[0,1]
	v_pk_mul_f32 v[42:43], v[106:107], v[42:43] op_sel:[1,0] op_sel_hi:[0,1]
	v_pk_fma_f32 v[40:41], v[108:109], v[56:57], v[40:41]
	v_pk_fma_f32 v[42:43], v[106:107], v[44:45], v[42:43]
	v_pk_add_f32 v[2:3], v[102:103], v[2:3]
	v_pk_add_f32 v[40:41], v[40:41], v[42:43]
	v_pk_mov_b32 v[42:43], v[20:21], v[24:25] op_sel:[1,0]
	v_mov_b32_e32 v21, v25
	v_pk_mov_b32 v[24:25], v[22:23], v[26:27] op_sel:[1,0]
	v_mov_b32_e32 v23, v27
	v_pk_mul_f32 v[20:21], v[108:109], v[20:21] op_sel:[1,0] op_sel_hi:[0,1]
	v_pk_mul_f32 v[22:23], v[106:107], v[22:23] op_sel:[1,0] op_sel_hi:[0,1]
	v_pk_fma_f32 v[20:21], v[108:109], v[42:43], v[20:21]
	v_pk_fma_f32 v[22:23], v[106:107], v[24:25], v[22:23]
	v_pk_add_f32 v[40:41], v[100:101], v[40:41]
	v_pk_add_f32 v[20:21], v[20:21], v[22:23]
	v_pk_mov_b32 v[22:23], v[12:13], v[16:17] op_sel:[1,0]
	v_mov_b32_e32 v13, v17
	v_pk_mov_b32 v[16:17], v[14:15], v[18:19] op_sel:[1,0]
	v_mov_b32_e32 v15, v19
	v_pk_mul_f32 v[12:13], v[108:109], v[12:13] op_sel:[1,0] op_sel_hi:[0,1]
	v_pk_mul_f32 v[14:15], v[106:107], v[14:15] op_sel:[1,0] op_sel_hi:[0,1]
	v_pk_fma_f32 v[12:13], v[108:109], v[22:23], v[12:13]
	v_pk_fma_f32 v[14:15], v[106:107], v[16:17], v[14:15]
	v_pk_add_f32 v[20:21], v[98:99], v[20:21]
	v_pk_add_f32 v[12:13], v[12:13], v[14:15]
	v_pk_mov_b32 v[14:15], v[4:5], v[8:9] op_sel:[1,0]
	v_mov_b32_e32 v5, v9
	v_pk_mov_b32 v[8:9], v[6:7], v[10:11] op_sel:[1,0]
	v_mov_b32_e32 v7, v11
	v_pk_mul_f32 v[4:5], v[108:109], v[4:5] op_sel:[1,0] op_sel_hi:[0,1]
	v_pk_mul_f32 v[6:7], v[106:107], v[6:7] op_sel:[1,0] op_sel_hi:[0,1]
	v_pk_fma_f32 v[4:5], v[108:109], v[14:15], v[4:5]
	v_pk_fma_f32 v[6:7], v[106:107], v[8:9], v[6:7]
	v_pk_add_f32 v[12:13], v[96:97], v[12:13]
	v_pk_add_f32 v[4:5], v[4:5], v[6:7]
	v_pk_mov_b32 v[6:7], v[48:49], v[52:53] op_sel:[1,0]
	v_mov_b32_e32 v49, v53
	v_pk_mul_f32 v[8:9], v[108:109], v[48:49] op_sel:[1,0] op_sel_hi:[0,1]
	v_pk_fma_f32 v[6:7], v[108:109], v[6:7], v[8:9]
	v_pk_mov_b32 v[8:9], v[50:51], v[54:55] op_sel:[1,0]
	v_mov_b32_e32 v51, v55
	v_pk_mul_f32 v[10:11], v[106:107], v[50:51] op_sel:[1,0] op_sel_hi:[0,1]
	v_pk_fma_f32 v[8:9], v[106:107], v[8:9], v[10:11]
	v_pk_add_f32 v[4:5], v[94:95], v[4:5]
	v_pk_add_f32 v[6:7], v[6:7], v[8:9]
	v_pk_mov_b32 v[8:9], v[32:33], v[36:37] op_sel:[1,0]
	v_mov_b32_e32 v33, v37
	v_pk_mul_f32 v[10:11], v[108:109], v[32:33] op_sel:[1,0] op_sel_hi:[0,1]
	v_pk_fma_f32 v[8:9], v[108:109], v[8:9], v[10:11]
	v_pk_mov_b32 v[10:11], v[34:35], v[38:39] op_sel:[1,0]
	v_mov_b32_e32 v35, v39
	v_pk_mul_f32 v[14:15], v[106:107], v[34:35] op_sel:[1,0] op_sel_hi:[0,1]
	v_pk_fma_f32 v[10:11], v[106:107], v[10:11], v[14:15]
	v_pk_add_f32 v[6:7], v[92:93], v[6:7]
	v_pk_add_f32 v[8:9], v[8:9], v[10:11]
	s_nop 0
	v_pk_add_f32 v[18:19], v[86:87], v[8:9]
	v_mov_b32_e32 v8, v29
	v_mov_b32_e32 v29, v31
	v_mov_b32_e32 v9, v30
	v_pk_mul_f32 v[10:11], v[148:149], v[28:29]
	s_nop 0
	v_pk_fma_f32 v[8:9], v[150:151], v[8:9], v[10:11]
	s_nop 0
	v_add_f32_e32 v8, v8, v9
	v_add_f32_e32 v77, v77, v8
	v_add_co_u32_e32 v8, vcc, s0, v84
	s_mov_b32 s0, 0x66000
	s_nop 0
	v_addc_co_u32_e32 v9, vcc, 0, v85, vcc
	v_add_co_u32_e32 v8, vcc, s0, v84
	s_mov_b32 s0, 0x6c000
	s_nop 0
	v_addc_co_u32_e32 v9, vcc, 0, v85, vcc
	v_add_co_u32_e32 v8, vcc, s0, v84
	s_mov_b32 s0, 0x72000
	s_nop 0
	v_addc_co_u32_e32 v9, vcc, 0, v85, vcc
	v_add_co_u32_e32 v8, vcc, s0, v84
	s_mov_b32 s0, 0x78000
	s_nop 0
	v_addc_co_u32_e32 v9, vcc, 0, v85, vcc
	ds_read_b128 v[8:11], v70 offset:64
	ds_read_b128 v[14:17], v70 offset:576
	ds_read_b128 v[22:25], v70 offset:1088
	ds_read_b128 v[26:29], v70 offset:1600
	ds_read_b128 v[30:33], v70 offset:2112
	ds_read_b128 v[34:37], v70 offset:2624
	ds_read_b128 v[42:45], v70 offset:3136
	ds_read_b128 v[46:49], v70 offset:3648
	ds_read_b128 v[50:53], v70 offset:4160
	ds_read_b128 v[54:57], v70 offset:4672
	ds_read_b128 v[58:61], v70 offset:5184
	ds_read_b128 v[62:65], v70 offset:5696
	ds_read_b128 v[94:97], v70 offset:6208
	ds_read_b128 v[98:101], v70 offset:6720
	ds_read_b128 v[102:105], v70 offset:7232
	ds_read_b128 v[106:109], v70 offset:7744
	ds_read_b128 v[118:121], v70 offset:8256
	s_waitcnt lgkmcnt(0)
	v_pk_mov_b32 v[66:67], v[8:9], v[14:15] op_sel:[1,0]
	v_mov_b32_e32 v9, v15
	v_pk_mov_b32 v[14:15], v[10:11], v[16:17] op_sel:[1,0]
	v_mov_b32_e32 v11, v17
	s_waitcnt vmcnt(12)
; #define LAS __attribute__((address_space(3)))
; __device__ __forceinline__ void phase0(Ctx& C, int mask) {
;     ...
; #pragma unroll 8
;                 for (int k4 = 0; k4 < 16; ++k4) { const int kl = 64 * kh + 4 * k4; float wv[4];
; #pragma unroll
;                     for (int q = 0; q < 4; ++q) wv[q] = __builtin_nontemporal_load(w_ada + (size_t)(128 * C.wave + kl + q) * 6144 + col);
; #pragma unroll
;                     for (int r = 0; r < 17; ++r) { const f4 s4 = *(const LAS f4*)(sil + r * 128 + kl); acc[r] += (s4[0] * wv[0] + s4[1] * wv[1]) + (s4[2] * wv[2] + s4[3] * wv[3]); } }
	v_mov_b32_e32 v127, v152
	v_mov_b32_e32 v126, v154
	v_pk_mul_f32 v[8:9], v[126:127], v[8:9] op_sel:[1,0] op_sel_hi:[0,1]
	v_pk_fma_f32 v[8:9], v[126:127], v[66:67], v[8:9]
	v_mov_b32_e32 v125, v155
	v_mov_b32_e32 v124, v153
	v_pk_mul_f32 v[10:11], v[124:125], v[10:11] op_sel:[1,0] op_sel_hi:[0,1]
	v_pk_fma_f32 v[10:11], v[124:125], v[14:15], v[10:11]
	s_nop 0
	v_pk_add_f32 v[8:9], v[8:9], v[10:11]
	s_nop 0
	v_pk_add_f32 v[92:93], v[0:1], v[8:9]
	v_pk_mov_b32 v[0:1], v[22:23], v[26:27] op_sel:[1,0]
	v_mov_b32_e32 v23, v27
	v_pk_mul_f32 v[8:9], v[126:127], v[22:23] op_sel:[1,0] op_sel_hi:[0,1]
	v_pk_fma_f32 v[0:1], v[126:127], v[0:1], v[8:9]
	v_pk_mov_b32 v[8:9], v[24:25], v[28:29] op_sel:[1,0]
	v_mov_b32_e32 v25, v29
	v_pk_mul_f32 v[10:11], v[124:125], v[24:25] op_sel:[1,0] op_sel_hi:[0,1]
	v_pk_fma_f32 v[8:9], v[124:125], v[8:9], v[10:11]
	s_nop 0
	v_pk_add_f32 v[0:1], v[0:1], v[8:9]
	s_nop 0
	v_pk_add_f32 v[90:91], v[2:3], v[0:1]
	v_pk_mov_b32 v[0:1], v[30:31], v[34:35] op_sel:[1,0]
	v_mov_b32_e32 v31, v35
	v_pk_mul_f32 v[2:3], v[126:127], v[30:31] op_sel:[1,0] op_sel_hi:[0,1]
	v_pk_fma_f32 v[0:1], v[126:127], v[0:1], v[2:3]
	v_pk_mov_b32 v[2:3], v[32:33], v[36:37] op_sel:[1,0]
	v_mov_b32_e32 v33, v37
	v_pk_mul_f32 v[8:9], v[124:125], v[32:33] op_sel:[1,0] op_sel_hi:[0,1]
	v_pk_fma_f32 v[2:3], v[124:125], v[2:3], v[8:9]
	s_nop 0
	v_pk_add_f32 v[0:1], v[0:1], v[2:3]
	s_nop 0
	v_pk_add_f32 v[88:89], v[40:41], v[0:1]
	v_pk_mov_b32 v[0:1], v[42:43], v[46:47] op_sel:[1,0]
	v_mov_b32_e32 v43, v47
	v_pk_mul_f32 v[2:3], v[126:127], v[42:43] op_sel:[1,0] op_sel_hi:[0,1]
	v_pk_fma_f32 v[0:1], v[126:127], v[0:1], v[2:3]
	v_pk_mov_b32 v[2:3], v[44:45], v[48:49] op_sel:[1,0]
	v_mov_b32_e32 v45, v49
	v_pk_mul_f32 v[8:9], v[124:125], v[44:45] op_sel:[1,0] op_sel_hi:[0,1]
	v_pk_fma_f32 v[2:3], v[124:125], v[2:3], v[8:9]
	s_nop 0
	v_pk_add_f32 v[0:1], v[0:1], v[2:3]
	s_nop 0
	v_pk_add_f32 v[86:87], v[20:21], v[0:1]
	v_pk_mov_b32 v[0:1], v[50:51], v[54:55] op_sel:[1,0]
	v_mov_b32_e32 v51, v55
	v_pk_mul_f32 v[2:3], v[126:127], v[50:51] op_sel:[1,0] op_sel_hi:[0,1]
	v_pk_fma_f32 v[0:1], v[126:127], v[0:1], v[2:3]
	v_pk_mov_b32 v[2:3], v[52:53], v[56:57] op_sel:[1,0]
	v_mov_b32_e32 v53, v57
	v_pk_mul_f32 v[8:9], v[124:125], v[52:53] op_sel:[1,0] op_sel_hi:[0,1]
	v_pk_fma_f32 v[2:3], v[124:125], v[2:3], v[8:9]
	s_nop 0
	v_pk_add_f32 v[0:1], v[0:1], v[2:3]
	s_nop 0
	v_pk_add_f32 v[66:67], v[12:13], v[0:1]
	v_pk_mov_b32 v[0:1], v[58:59], v[62:63] op_sel:[1,0]
	v_mov_b32_e32 v59, v63
	v_pk_mul_f32 v[2:3], v[126:127], v[58:59] op_sel:[1,0] op_sel_hi:[0,1]
	v_pk_fma_f32 v[0:1], v[126:127], v[0:1], v[2:3]
	v_pk_mov_b32 v[2:3], v[60:61], v[64:65] op_sel:[1,0]
	v_mov_b32_e32 v61, v65
	v_pk_mul_f32 v[8:9], v[124:125], v[60:61] op_sel:[1,0] op_sel_hi:[0,1]
	v_pk_fma_f32 v[2:3], v[124:125], v[2:3], v[8:9]
	s_nop 0
	v_pk_add_f32 v[0:1], v[0:1], v[2:3]
	s_nop 0
	v_pk_add_f32 v[64:65], v[4:5], v[0:1]
	v_pk_mov_b32 v[0:1], v[94:95], v[98:99] op_sel:[1,0]
	v_mov_b32_e32 v95, v99
	v_pk_mul_f32 v[2:3], v[126:127], v[94:95] op_sel:[1,0] op_sel_hi:[0,1]
	v_pk_fma_f32 v[0:1], v[126:127], v[0:1], v[2:3]
	v_pk_mov_b32 v[2:3], v[96:97], v[100:101] op_sel:[1,0]
	v_mov_b32_e32 v97, v101
	v_pk_mul_f32 v[4:5], v[124:125], v[96:97] op_sel:[1,0] op_sel_hi:[0,1]
	v_pk_fma_f32 v[2:3], v[124:125], v[2:3], v[4:5]
	s_nop 0
	v_pk_add_f32 v[0:1], v[0:1], v[2:3]
	s_nop 0
	v_pk_add_f32 v[62:63], v[6:7], v[0:1]
	v_pk_mov_b32 v[0:1], v[102:103], v[106:107] op_sel:[1,0]
	v_mov_b32_e32 v103, v107
	v_pk_mul_f32 v[2:3], v[126:127], v[102:103] op_sel:[1,0] op_sel_hi:[0,1]
	v_pk_fma_f32 v[0:1], v[126:127], v[0:1], v[2:3]
	v_pk_mov_b32 v[2:3], v[104:105], v[108:109] op_sel:[1,0]
	v_mov_b32_e32 v105, v109
	v_pk_mul_f32 v[4:5], v[124:125], v[104:105] op_sel:[1,0] op_sel_hi:[0,1]
	v_pk_fma_f32 v[2:3], v[124:125], v[2:3], v[4:5]
	s_nop 0
	v_pk_add_f32 v[0:1], v[0:1], v[2:3]
	s_nop 0
	v_pk_add_f32 v[56:57], v[18:19], v[0:1]
	v_mov_b32_e32 v0, v119
	v_mov_b32_e32 v119, v121
	v_mov_b32_e32 v1, v120
	v_pk_mul_f32 v[2:3], v[152:153], v[118:119]
	s_nop 0
	v_pk_fma_f32 v[0:1], v[154:155], v[0:1], v[2:3]
	s_nop 0
	v_add_f32_e32 v0, v0, v1
	v_add_f32_e32 v77, v77, v0
	v_add_co_u32_e32 v0, vcc, s0, v84
	s_mov_b32 s0, 0x7e000
	s_nop 0
	v_addc_co_u32_e32 v1, vcc, 0, v85, vcc
	v_add_co_u32_e32 v0, vcc, s0, v84
	s_mov_b32 s0, 0x84000
	s_nop 0
	v_addc_co_u32_e32 v1, vcc, 0, v85, vcc
	v_add_co_u32_e32 v0, vcc, s0, v84
	s_mov_b32 s0, 0x8a000
	s_nop 0
	v_addc_co_u32_e32 v1, vcc, 0, v85, vcc
	v_add_co_u32_e32 v0, vcc, s0, v84
	s_mov_b32 s0, 0x90000
	s_nop 0
	v_addc_co_u32_e32 v1, vcc, 0, v85, vcc
	ds_read_b128 v[98:101], v70 offset:80
	ds_read_b128 v[102:105], v70 offset:592
	ds_read_b128 v[52:55], v70 offset:1104
	ds_read_b128 v[106:109], v70 offset:1616
	ds_read_b128 v[44:47], v70 offset:2128
	ds_read_b128 v[48:51], v70 offset:2640
	ds_read_b128 v[36:39], v70 offset:3152
	ds_read_b128 v[40:43], v70 offset:3664
	ds_read_b128 v[28:31], v70 offset:4176
	ds_read_b128 v[32:35], v70 offset:4688
	ds_read_b128 v[20:23], v70 offset:5200
	ds_read_b128 v[24:27], v70 offset:5712
	ds_read_b128 v[12:15], v70 offset:6224
	ds_read_b128 v[16:19], v70 offset:6736
	ds_read_b128 v[4:7], v70 offset:7248
	ds_read_b128 v[8:11], v70 offset:7760
	ds_read_b128 v[0:3], v70 offset:8272
	s_waitcnt lgkmcnt(0)
	v_pk_mov_b32 v[118:119], v[98:99], v[102:103] op_sel:[1,0]
	v_mov_b32_e32 v99, v103
	v_pk_mov_b32 v[102:103], v[100:101], v[104:105] op_sel:[1,0]
	v_mov_b32_e32 v101, v105
	s_waitcnt vmcnt(8)
; #define LAS __attribute__((address_space(3)))
; __device__ __forceinline__ void phase0(Ctx& C, int mask) {
;     ...
; #pragma unroll 8
;                 for (int k4 = 0; k4 < 16; ++k4) { const int kl = 64 * kh + 4 * k4; float wv[4];
; #pragma unroll
;                     for (int q = 0; q < 4; ++q) wv[q] = __builtin_nontemporal_load(w_ada + (size_t)(128 * C.wave + kl + q) * 6144 + col);
; #pragma unroll
;                     for (int r = 0; r < 17; ++r) { const f4 s4 = *(const LAS f4*)(sil + r * 128 + kl); acc[r] += (s4[0] * wv[0] + s4[1] * wv[1]) + (s4[2] * wv[2] + s4[3] * wv[3]); } }
	v_mov_b32_e32 v97, v156
	v_mov_b32_e32 v96, v158
	v_pk_mul_f32 v[98:99], v[96:97], v[98:99] op_sel:[1,0] op_sel_hi:[0,1]
	v_pk_fma_f32 v[98:99], v[96:97], v[118:119], v[98:99]
	v_mov_b32_e32 v95, v159
	v_mov_b32_e32 v94, v157
	v_pk_mul_f32 v[100:101], v[94:95], v[100:101] op_sel:[1,0] op_sel_hi:[0,1]
	v_pk_fma_f32 v[100:101], v[94:95], v[102:103], v[100:101]
	s_nop 0
	v_pk_add_f32 v[98:99], v[98:99], v[100:101]
	s_nop 0
	v_pk_add_f32 v[92:93], v[92:93], v[98:99]
	v_pk_mov_b32 v[98:99], v[52:53], v[106:107] op_sel:[1,0]
	v_mov_b32_e32 v53, v107
	v_pk_mul_f32 v[52:53], v[96:97], v[52:53] op_sel:[1,0] op_sel_hi:[0,1]
	v_pk_fma_f32 v[52:53], v[96:97], v[98:99], v[52:53]
	v_pk_mov_b32 v[98:99], v[54:55], v[108:109] op_sel:[1,0]
	v_mov_b32_e32 v55, v109
	v_pk_mul_f32 v[54:55], v[94:95], v[54:55] op_sel:[1,0] op_sel_hi:[0,1]
	v_pk_fma_f32 v[54:55], v[94:95], v[98:99], v[54:55]
	s_nop 0
	v_pk_add_f32 v[52:53], v[52:53], v[54:55]
	v_pk_mov_b32 v[54:55], v[44:45], v[48:49] op_sel:[1,0]
	v_mov_b32_e32 v45, v49
	v_pk_mov_b32 v[48:49], v[46:47], v[50:51] op_sel:[1,0]
	v_mov_b32_e32 v47, v51
	v_pk_mul_f32 v[44:45], v[96:97], v[44:45] op_sel:[1,0] op_sel_hi:[0,1]
	v_pk_mul_f32 v[46:47], v[94:95], v[46:47] op_sel:[1,0] op_sel_hi:[0,1]
	v_pk_fma_f32 v[44:45], v[96:97], v[54:55], v[44:45]
	v_pk_fma_f32 v[46:47], v[94:95], v[48:49], v[46:47]
	v_pk_add_f32 v[52:53], v[90:91], v[52:53]
	v_pk_add_f32 v[44:45], v[44:45], v[46:47]
	v_pk_mov_b32 v[46:47], v[36:37], v[40:41] op_sel:[1,0]
	v_mov_b32_e32 v37, v41
	v_pk_mov_b32 v[40:41], v[38:39], v[42:43] op_sel:[1,0]
	v_mov_b32_e32 v39, v43
	v_pk_mul_f32 v[36:37], v[96:97], v[36:37] op_sel:[1,0] op_sel_hi:[0,1]
	v_pk_mul_f32 v[38:39], v[94:95], v[38:39] op_sel:[1,0] op_sel_hi:[0,1]
	v_pk_fma_f32 v[36:37], v[96:97], v[46:47], v[36:37]
	v_pk_fma_f32 v[38:39], v[94:95], v[40:41], v[38:39]
	v_pk_add_f32 v[44:45], v[88:89], v[44:45]
	v_pk_add_f32 v[36:37], v[36:37], v[38:39]
	v_pk_mov_b32 v[38:39], v[28:29], v[32:33] op_sel:[1,0]
	v_mov_b32_e32 v29, v33
	v_pk_mov_b32 v[32:33], v[30:31], v[34:35] op_sel:[1,0]
	v_mov_b32_e32 v31, v35
	v_pk_mul_f32 v[28:29], v[96:97], v[28:29] op_sel:[1,0] op_sel_hi:[0,1]
	v_pk_mul_f32 v[30:31], v[94:95], v[30:31] op_sel:[1,0] op_sel_hi:[0,1]
	v_pk_fma_f32 v[28:29], v[96:97], v[38:39], v[28:29]
	v_pk_fma_f32 v[30:31], v[94:95], v[32:33], v[30:31]
	v_pk_add_f32 v[36:37], v[86:87], v[36:37]
	v_pk_add_f32 v[28:29], v[28:29], v[30:31]
	v_pk_mov_b32 v[30:31], v[20:21], v[24:25] op_sel:[1,0]
	v_mov_b32_e32 v21, v25
	v_pk_mov_b32 v[24:25], v[22:23], v[26:27] op_sel:[1,0]
	v_mov_b32_e32 v23, v27
	v_pk_mul_f32 v[20:21], v[96:97], v[20:21] op_sel:[1,0] op_sel_hi:[0,1]
	v_pk_mul_f32 v[22:23], v[94:95], v[22:23] op_sel:[1,0] op_sel_hi:[0,1]
	v_pk_fma_f32 v[20:21], v[96:97], v[30:31], v[20:21]
	v_pk_fma_f32 v[22:23], v[94:95], v[24:25], v[22:23]
	v_pk_add_f32 v[28:29], v[66:67], v[28:29]
	v_pk_add_f32 v[20:21], v[20:21], v[22:23]
	v_pk_mov_b32 v[22:23], v[12:13], v[16:17] op_sel:[1,0]
	v_mov_b32_e32 v13, v17
	v_pk_mov_b32 v[16:17], v[14:15], v[18:19] op_sel:[1,0]
	v_mov_b32_e32 v15, v19
	v_pk_mul_f32 v[12:13], v[96:97], v[12:13] op_sel:[1,0] op_sel_hi:[0,1]
	v_pk_mul_f32 v[14:15], v[94:95], v[14:15] op_sel:[1,0] op_sel_hi:[0,1]
	v_pk_fma_f32 v[12:13], v[96:97], v[22:23], v[12:13]
	v_pk_fma_f32 v[14:15], v[94:95], v[16:17], v[14:15]
	v_pk_add_f32 v[20:21], v[64:65], v[20:21]
	v_pk_add_f32 v[12:13], v[12:13], v[14:15]
	v_pk_mov_b32 v[14:15], v[4:5], v[8:9] op_sel:[1,0]
	v_mov_b32_e32 v5, v9
	v_pk_mov_b32 v[8:9], v[6:7], v[10:11] op_sel:[1,0]
	v_mov_b32_e32 v7, v11
	v_pk_mul_f32 v[4:5], v[96:97], v[4:5] op_sel:[1,0] op_sel_hi:[0,1]
	v_pk_mul_f32 v[6:7], v[94:95], v[6:7] op_sel:[1,0] op_sel_hi:[0,1]
	v_pk_fma_f32 v[4:5], v[96:97], v[14:15], v[4:5]
	v_pk_fma_f32 v[6:7], v[94:95], v[8:9], v[6:7]
	v_pk_add_f32 v[12:13], v[62:63], v[12:13]
	v_pk_add_f32 v[4:5], v[4:5], v[6:7]
	s_nop 0
	v_pk_add_f32 v[18:19], v[56:57], v[4:5]
	v_mov_b32_e32 v4, v1
	v_mov_b32_e32 v1, v3
	v_mov_b32_e32 v5, v2
	v_pk_mul_f32 v[0:1], v[156:157], v[0:1]
	s_nop 0
	v_pk_fma_f32 v[0:1], v[158:159], v[4:5], v[0:1]
	s_nop 0
	v_add_f32_e32 v0, v0, v1
	v_add_f32_e32 v77, v77, v0
	v_add_co_u32_e32 v0, vcc, s0, v84
	s_mov_b32 s0, 0x96000
	s_nop 0
	v_addc_co_u32_e32 v1, vcc, 0, v85, vcc
	v_add_co_u32_e32 v0, vcc, s0, v84
	s_mov_b32 s0, 0x9c000
	s_nop 0
	v_addc_co_u32_e32 v1, vcc, 0, v85, vcc
	v_add_co_u32_e32 v0, vcc, s0, v84
	s_mov_b32 s0, 0xa2000
	s_nop 0
	v_addc_co_u32_e32 v1, vcc, 0, v85, vcc
	v_add_co_u32_e32 v0, vcc, s0, v84
	s_mov_b32 s0, 0xa8000
	s_nop 0
	v_addc_co_u32_e32 v1, vcc, 0, v85, vcc
	ds_read_b128 v[0:3], v70 offset:96
	ds_read_b128 v[4:7], v70 offset:608
	ds_read_b128 v[8:11], v70 offset:1120
	ds_read_b128 v[14:17], v70 offset:1632
	ds_read_b128 v[22:25], v70 offset:2144
	ds_read_b128 v[30:33], v70 offset:2656
	ds_read_b128 v[38:41], v70 offset:3168
	ds_read_b128 v[46:49], v70 offset:3680
	ds_read_b128 v[58:61], v70 offset:4192
	ds_read_b128 v[62:65], v70 offset:4704
	ds_read_b128 v[94:97], v70 offset:5216
	ds_read_b128 v[98:101], v70 offset:5728
	ds_read_b128 v[102:105], v70 offset:6240
	ds_read_b128 v[106:109], v70 offset:6752
	ds_read_b128 v[118:121], v70 offset:7264
	ds_read_b128 v[122:125], v70 offset:7776
	ds_read_b128 v[126:129], v70 offset:8288
	s_waitcnt lgkmcnt(0)
	v_pk_mov_b32 v[54:55], v[0:1], v[4:5] op_sel:[1,0]
	v_mov_b32_e32 v1, v5
	v_pk_mov_b32 v[4:5], v[2:3], v[6:7] op_sel:[1,0]
	v_mov_b32_e32 v3, v7
	s_waitcnt vmcnt(4)
; #define LAS __attribute__((address_space(3)))
; __device__ __forceinline__ void phase0(Ctx& C, int mask) {
;     ...
; #pragma unroll 8
;                 for (int k4 = 0; k4 < 16; ++k4) { const int kl = 64 * kh + 4 * k4; float wv[4];
; #pragma unroll
;                     for (int q = 0; q < 4; ++q) wv[q] = __builtin_nontemporal_load(w_ada + (size_t)(128 * C.wave + kl + q) * 6144 + col);
; #pragma unroll
;                     for (int r = 0; r < 17; ++r) { const f4 s4 = *(const LAS f4*)(sil + r * 128 + kl); acc[r] += (s4[0] * wv[0] + s4[1] * wv[1]) + (s4[2] * wv[2] + s4[3] * wv[3]); } }
	v_mov_b32_e32 v51, v160
	v_mov_b32_e32 v50, v162
	v_pk_mul_f32 v[0:1], v[50:51], v[0:1] op_sel:[1,0] op_sel_hi:[0,1]
	v_pk_fma_f32 v[0:1], v[50:51], v[54:55], v[0:1]
	v_mov_b32_e32 v43, v163
	v_mov_b32_e32 v42, v161
	v_pk_mul_f32 v[2:3], v[42:43], v[2:3] op_sel:[1,0] op_sel_hi:[0,1]
	v_pk_fma_f32 v[2:3], v[42:43], v[4:5], v[2:3]
	s_nop 0
	v_pk_add_f32 v[0:1], v[0:1], v[2:3]
	s_nop 0
	v_pk_add_f32 v[56:57], v[92:93], v[0:1]
	v_pk_mov_b32 v[0:1], v[8:9], v[14:15] op_sel:[1,0]
	v_mov_b32_e32 v9, v15
	v_pk_mul_f32 v[2:3], v[50:51], v[8:9] op_sel:[1,0] op_sel_hi:[0,1]
	v_pk_fma_f32 v[0:1], v[50:51], v[0:1], v[2:3]
	v_pk_mov_b32 v[2:3], v[10:11], v[16:17] op_sel:[1,0]
	v_mov_b32_e32 v11, v17
	v_pk_mul_f32 v[4:5], v[42:43], v[10:11] op_sel:[1,0] op_sel_hi:[0,1]
	v_pk_fma_f32 v[2:3], v[42:43], v[2:3], v[4:5]
	s_nop 0
	v_pk_add_f32 v[0:1], v[0:1], v[2:3]
	s_nop 0
	v_pk_add_f32 v[92:93], v[52:53], v[0:1]
	v_pk_mov_b32 v[0:1], v[22:23], v[30:31] op_sel:[1,0]
	v_mov_b32_e32 v23, v31
	v_pk_mul_f32 v[2:3], v[50:51], v[22:23] op_sel:[1,0] op_sel_hi:[0,1]
	v_pk_fma_f32 v[0:1], v[50:51], v[0:1], v[2:3]
	v_pk_mov_b32 v[2:3], v[24:25], v[32:33] op_sel:[1,0]
	v_mov_b32_e32 v25, v33
	v_pk_mul_f32 v[4:5], v[42:43], v[24:25] op_sel:[1,0] op_sel_hi:[0,1]
	v_pk_fma_f32 v[2:3], v[42:43], v[2:3], v[4:5]
	s_nop 0
	v_pk_add_f32 v[0:1], v[0:1], v[2:3]
	s_nop 0
	v_pk_add_f32 v[90:91], v[44:45], v[0:1]
	v_pk_mov_b32 v[0:1], v[38:39], v[46:47] op_sel:[1,0]
	v_mov_b32_e32 v39, v47
	v_pk_mul_f32 v[2:3], v[50:51], v[38:39] op_sel:[1,0] op_sel_hi:[0,1]
	v_pk_fma_f32 v[0:1], v[50:51], v[0:1], v[2:3]
	v_pk_mov_b32 v[2:3], v[40:41], v[48:49] op_sel:[1,0]
	v_mov_b32_e32 v41, v49
	v_pk_mul_f32 v[4:5], v[42:43], v[40:41] op_sel:[1,0] op_sel_hi:[0,1]
	v_pk_fma_f32 v[2:3], v[42:43], v[2:3], v[4:5]
	s_nop 0
	v_pk_add_f32 v[0:1], v[0:1], v[2:3]
	s_nop 0
	v_pk_add_f32 v[88:89], v[36:37], v[0:1]
	v_pk_mov_b32 v[0:1], v[58:59], v[62:63] op_sel:[1,0]
	v_mov_b32_e32 v59, v63
	v_pk_mul_f32 v[2:3], v[50:51], v[58:59] op_sel:[1,0] op_sel_hi:[0,1]
	v_pk_fma_f32 v[0:1], v[50:51], v[0:1], v[2:3]
	v_pk_mov_b32 v[2:3], v[60:61], v[64:65] op_sel:[1,0]
	v_mov_b32_e32 v61, v65
	v_pk_mul_f32 v[4:5], v[42:43], v[60:61] op_sel:[1,0] op_sel_hi:[0,1]
	v_pk_fma_f32 v[2:3], v[42:43], v[2:3], v[4:5]
	s_nop 0
	v_pk_add_f32 v[0:1], v[0:1], v[2:3]
	s_nop 0
	v_pk_add_f32 v[86:87], v[28:29], v[0:1]
	v_pk_mov_b32 v[0:1], v[94:95], v[98:99] op_sel:[1,0]
	v_mov_b32_e32 v95, v99
	v_pk_mul_f32 v[2:3], v[50:51], v[94:95] op_sel:[1,0] op_sel_hi:[0,1]
	v_pk_fma_f32 v[0:1], v[50:51], v[0:1], v[2:3]
	v_pk_mov_b32 v[2:3], v[96:97], v[100:101] op_sel:[1,0]
	v_mov_b32_e32 v97, v101
	v_pk_mul_f32 v[4:5], v[42:43], v[96:97] op_sel:[1,0] op_sel_hi:[0,1]
	v_pk_fma_f32 v[2:3], v[42:43], v[2:3], v[4:5]
	s_nop 0
	v_pk_add_f32 v[0:1], v[0:1], v[2:3]
	s_nop 0
	v_pk_add_f32 v[66:67], v[20:21], v[0:1]
	v_pk_mov_b32 v[0:1], v[102:103], v[106:107] op_sel:[1,0]
	v_mov_b32_e32 v103, v107
	v_pk_mul_f32 v[2:3], v[50:51], v[102:103] op_sel:[1,0] op_sel_hi:[0,1]
	v_pk_fma_f32 v[0:1], v[50:51], v[0:1], v[2:3]
	v_pk_mov_b32 v[2:3], v[104:105], v[108:109] op_sel:[1,0]
	v_mov_b32_e32 v105, v109
	v_pk_mul_f32 v[4:5], v[42:43], v[104:105] op_sel:[1,0] op_sel_hi:[0,1]
	v_pk_fma_f32 v[2:3], v[42:43], v[2:3], v[4:5]
	s_nop 0
	v_pk_add_f32 v[0:1], v[0:1], v[2:3]
	s_nop 0
	v_pk_add_f32 v[64:65], v[12:13], v[0:1]
	v_pk_mov_b32 v[0:1], v[118:119], v[122:123] op_sel:[1,0]
	v_mov_b32_e32 v119, v123
	v_pk_mul_f32 v[2:3], v[50:51], v[118:119] op_sel:[1,0] op_sel_hi:[0,1]
	v_pk_fma_f32 v[0:1], v[50:51], v[0:1], v[2:3]
	v_pk_mov_b32 v[2:3], v[120:121], v[124:125] op_sel:[1,0]
	v_mov_b32_e32 v121, v125
	v_pk_mul_f32 v[4:5], v[42:43], v[120:121] op_sel:[1,0] op_sel_hi:[0,1]
	v_pk_fma_f32 v[2:3], v[42:43], v[2:3], v[4:5]
	s_nop 0
	v_pk_add_f32 v[0:1], v[0:1], v[2:3]
	s_nop 0
	v_pk_add_f32 v[62:63], v[18:19], v[0:1]
	v_mov_b32_e32 v0, v127
	v_mov_b32_e32 v127, v129
	v_mov_b32_e32 v1, v128
	v_pk_mul_f32 v[2:3], v[160:161], v[126:127]
	s_nop 0
	v_pk_fma_f32 v[0:1], v[162:163], v[0:1], v[2:3]
	s_nop 0
	v_add_f32_e32 v0, v0, v1
	v_add_f32_e32 v77, v77, v0
	v_add_co_u32_e32 v0, vcc, s0, v84
	s_mov_b32 s0, 0xae000
	s_nop 0
	v_addc_co_u32_e32 v1, vcc, 0, v85, vcc
	v_add_co_u32_e32 v0, vcc, s0, v84
	s_mov_b32 s0, 0xb4000
	s_nop 0
	v_addc_co_u32_e32 v1, vcc, 0, v85, vcc
	v_add_co_u32_e32 v0, vcc, s0, v84
	s_mov_b32 s0, 0xba000
	s_nop 0
	v_addc_co_u32_e32 v1, vcc, 0, v85, vcc
	v_add_co_u32_e32 v0, vcc, s0, v84
	s_waitcnt vmcnt(1) lgkmcnt(0)
	v_mov_b32_e32 v95, v164
	v_addc_co_u32_e32 v1, vcc, 0, v85, vcc
	ds_read_b128 v[96:99], v70 offset:112
	ds_read_b128 v[100:103], v70 offset:624
	ds_read_b128 v[52:55], v70 offset:1136
	ds_read_b128 v[104:107], v70 offset:1648
	ds_read_b128 v[44:47], v70 offset:2160
	ds_read_b128 v[48:51], v70 offset:2672
	ds_read_b128 v[36:39], v70 offset:3184
	ds_read_b128 v[40:43], v70 offset:3696
	ds_read_b128 v[28:31], v70 offset:4208
	ds_read_b128 v[32:35], v70 offset:4720
	ds_read_b128 v[20:23], v70 offset:5232
	ds_read_b128 v[24:27], v70 offset:5744
	ds_read_b128 v[12:15], v70 offset:6256
	ds_read_b128 v[16:19], v70 offset:6768
	ds_read_b128 v[4:7], v70 offset:7280
	ds_read_b128 v[8:11], v70 offset:7792
	ds_read_b128 v[0:3], v70 offset:8304
	s_waitcnt lgkmcnt(0)
	v_pk_mov_b32 v[108:109], v[96:97], v[100:101] op_sel:[1,0]
	v_mov_b32_e32 v94, v166
	v_mov_b32_e32 v97, v101
	v_pk_mov_b32 v[100:101], v[98:99], v[102:103] op_sel:[1,0]
	v_mov_b32_e32 v99, v103
	v_pk_mul_f32 v[96:97], v[94:95], v[96:97] op_sel:[1,0] op_sel_hi:[0,1]
	v_pk_fma_f32 v[96:97], v[94:95], v[108:109], v[96:97]
	v_mov_b32_e32 v85, v167
	v_add_u32_e32 v70, 0x80, v70
	s_waitcnt vmcnt(0)
; #define LAS __attribute__((address_space(3)))
; __device__ __forceinline__ void phase0(Ctx& C, int mask) {
;     ...
; #pragma unroll 8
;                 for (int k4 = 0; k4 < 16; ++k4) { const int kl = 64 * kh + 4 * k4; float wv[4];
; #pragma unroll
;                     for (int q = 0; q < 4; ++q) wv[q] = __builtin_nontemporal_load(w_ada + (size_t)(128 * C.wave + kl + q) * 6144 + col);
; #pragma unroll
;                     for (int r = 0; r < 17; ++r) { const f4 s4 = *(const LAS f4*)(sil + r * 128 + kl); acc[r] += (s4[0] * wv[0] + s4[1] * wv[1]) + (s4[2] * wv[2] + s4[3] * wv[3]); } }
; #pragma unroll
;                 for (int r = 0; r < 17; ++r) acc[r] += __shfl_xor(acc[r], 32);
;                 __syncthreads();
;                 if (C.lane < 32) {
; #pragma unroll
;                     for (int r = 0; r < 17; ++r) red[(C.wave * 17 + r) * 32 + C.lane] = acc[r];
;                 }
	v_mov_b32_e32 v84, v165
	v_pk_mul_f32 v[98:99], v[84:85], v[98:99] op_sel:[1,0] op_sel_hi:[0,1]
	v_pk_fma_f32 v[98:99], v[84:85], v[100:101], v[98:99]
	s_nop 0
	v_pk_add_f32 v[96:97], v[96:97], v[98:99]
	s_nop 0
	v_pk_add_f32 v[56:57], v[56:57], v[96:97]
	v_pk_mov_b32 v[96:97], v[52:53], v[104:105] op_sel:[1,0]
	v_mov_b32_e32 v53, v105
	v_pk_mul_f32 v[52:53], v[94:95], v[52:53] op_sel:[1,0] op_sel_hi:[0,1]
	v_pk_fma_f32 v[52:53], v[94:95], v[96:97], v[52:53]
	v_pk_mov_b32 v[96:97], v[54:55], v[106:107] op_sel:[1,0]
	v_mov_b32_e32 v55, v107
	v_pk_mul_f32 v[54:55], v[84:85], v[54:55] op_sel:[1,0] op_sel_hi:[0,1]
	v_pk_fma_f32 v[54:55], v[84:85], v[96:97], v[54:55]
	s_nop 0
	v_pk_add_f32 v[52:53], v[52:53], v[54:55]
	v_pk_mov_b32 v[54:55], v[44:45], v[48:49] op_sel:[1,0]
	v_mov_b32_e32 v45, v49
	v_pk_mov_b32 v[48:49], v[46:47], v[50:51] op_sel:[1,0]
	v_mov_b32_e32 v47, v51
	v_pk_mul_f32 v[44:45], v[94:95], v[44:45] op_sel:[1,0] op_sel_hi:[0,1]
	v_pk_mul_f32 v[46:47], v[84:85], v[46:47] op_sel:[1,0] op_sel_hi:[0,1]
	v_pk_fma_f32 v[44:45], v[94:95], v[54:55], v[44:45]
	v_pk_fma_f32 v[46:47], v[84:85], v[48:49], v[46:47]
	v_pk_add_f32 v[52:53], v[92:93], v[52:53]
	v_pk_add_f32 v[44:45], v[44:45], v[46:47]
	v_pk_mov_b32 v[46:47], v[36:37], v[40:41] op_sel:[1,0]
	v_mov_b32_e32 v37, v41
	v_pk_mov_b32 v[40:41], v[38:39], v[42:43] op_sel:[1,0]
	v_mov_b32_e32 v39, v43
	v_pk_mul_f32 v[36:37], v[94:95], v[36:37] op_sel:[1,0] op_sel_hi:[0,1]
	v_pk_mul_f32 v[38:39], v[84:85], v[38:39] op_sel:[1,0] op_sel_hi:[0,1]
	v_pk_fma_f32 v[36:37], v[94:95], v[46:47], v[36:37]
	v_pk_fma_f32 v[38:39], v[84:85], v[40:41], v[38:39]
	v_pk_add_f32 v[44:45], v[90:91], v[44:45]
	v_pk_add_f32 v[36:37], v[36:37], v[38:39]
	v_pk_mov_b32 v[38:39], v[28:29], v[32:33] op_sel:[1,0]
	v_mov_b32_e32 v29, v33
	v_pk_mov_b32 v[32:33], v[30:31], v[34:35] op_sel:[1,0]
	v_mov_b32_e32 v31, v35
	v_pk_mul_f32 v[28:29], v[94:95], v[28:29] op_sel:[1,0] op_sel_hi:[0,1]
	v_pk_mul_f32 v[30:31], v[84:85], v[30:31] op_sel:[1,0] op_sel_hi:[0,1]
	v_pk_fma_f32 v[28:29], v[94:95], v[38:39], v[28:29]
	v_pk_fma_f32 v[30:31], v[84:85], v[32:33], v[30:31]
	v_pk_add_f32 v[36:37], v[88:89], v[36:37]
	v_pk_add_f32 v[28:29], v[28:29], v[30:31]
	v_pk_mov_b32 v[30:31], v[20:21], v[24:25] op_sel:[1,0]
	v_mov_b32_e32 v21, v25
	v_pk_mov_b32 v[24:25], v[22:23], v[26:27] op_sel:[1,0]
	v_mov_b32_e32 v23, v27
	v_pk_mul_f32 v[20:21], v[94:95], v[20:21] op_sel:[1,0] op_sel_hi:[0,1]
	v_pk_mul_f32 v[22:23], v[84:85], v[22:23] op_sel:[1,0] op_sel_hi:[0,1]
	v_pk_fma_f32 v[20:21], v[94:95], v[30:31], v[20:21]
	v_pk_fma_f32 v[22:23], v[84:85], v[24:25], v[22:23]
	v_pk_add_f32 v[28:29], v[86:87], v[28:29]
	v_pk_add_f32 v[20:21], v[20:21], v[22:23]
	v_pk_mov_b32 v[22:23], v[12:13], v[16:17] op_sel:[1,0]
	v_mov_b32_e32 v13, v17
	v_pk_mov_b32 v[16:17], v[14:15], v[18:19] op_sel:[1,0]
	v_mov_b32_e32 v15, v19
	v_pk_mul_f32 v[12:13], v[94:95], v[12:13] op_sel:[1,0] op_sel_hi:[0,1]
	v_pk_mul_f32 v[14:15], v[84:85], v[14:15] op_sel:[1,0] op_sel_hi:[0,1]
	v_pk_fma_f32 v[12:13], v[94:95], v[22:23], v[12:13]
	v_pk_fma_f32 v[14:15], v[84:85], v[16:17], v[14:15]
	v_pk_add_f32 v[20:21], v[66:67], v[20:21]
	v_pk_add_f32 v[12:13], v[12:13], v[14:15]
	v_pk_mov_b32 v[14:15], v[4:5], v[8:9] op_sel:[1,0]
	v_mov_b32_e32 v5, v9
	v_pk_mov_b32 v[8:9], v[6:7], v[10:11] op_sel:[1,0]
	v_mov_b32_e32 v7, v11
	v_pk_mul_f32 v[4:5], v[94:95], v[4:5] op_sel:[1,0] op_sel_hi:[0,1]
	v_pk_mul_f32 v[6:7], v[84:85], v[6:7] op_sel:[1,0] op_sel_hi:[0,1]
	v_pk_fma_f32 v[4:5], v[94:95], v[14:15], v[4:5]
	v_pk_fma_f32 v[6:7], v[84:85], v[8:9], v[6:7]
	v_pk_add_f32 v[12:13], v[64:65], v[12:13]
	v_pk_add_f32 v[4:5], v[4:5], v[6:7]
	s_nop 0
	v_pk_add_f32 v[14:15], v[62:63], v[4:5]
	v_mov_b32_e32 v4, v1
	v_mov_b32_e32 v1, v3
	v_mov_b32_e32 v5, v2
	v_pk_mul_f32 v[0:1], v[164:165], v[0:1]
	s_nop 0
	v_pk_fma_f32 v[0:1], v[166:167], v[4:5], v[0:1]
	s_nop 0
	v_add_f32_e32 v0, v0, v1
	v_add_f32_e32 v30, v77, v0
	s_cbranch_scc0 .LBB0_154
	v_and_b32_e32 v1, 64, v115
	v_xor_b32_e32 v0, 32, v115
	v_add_u32_e32 v1, 64, v1
	v_cmp_lt_i32_e32 vcc, v0, v1
	s_barrier
	s_nop 0
	v_cndmask_b32_e32 v0, v115, v0, vcc
	v_lshlrev_b32_e32 v22, 2, v0
	ds_bpermute_b32 v0, v22, v56
	ds_bpermute_b32 v1, v22, v57
	ds_bpermute_b32 v2, v22, v52
	ds_bpermute_b32 v3, v22, v53
	ds_bpermute_b32 v4, v22, v44
	ds_bpermute_b32 v5, v22, v45
	ds_bpermute_b32 v6, v22, v36
	ds_bpermute_b32 v7, v22, v37
	ds_bpermute_b32 v8, v22, v28
	ds_bpermute_b32 v9, v22, v29
	ds_bpermute_b32 v10, v22, v20
	ds_bpermute_b32 v11, v22, v21
	ds_bpermute_b32 v16, v22, v12
	ds_bpermute_b32 v17, v22, v13
	ds_bpermute_b32 v18, v22, v14
	ds_bpermute_b32 v19, v22, v15
	ds_bpermute_b32 v22, v22, v30
	s_waitcnt lgkmcnt(0)
	s_and_saveexec_b64 s[6:7], s[4:5]
	s_cbranch_execz .LBB0_157
	v_add_f32_e32 v1, v57, v1
	v_add_f32_e32 v0, v56, v0
	v_add_f32_e32 v9, v29, v9
	v_add_f32_e32 v8, v28, v8
	v_add_f32_e32 v7, v37, v7
	v_add_f32_e32 v6, v36, v6
	v_add_f32_e32 v5, v45, v5
	v_add_f32_e32 v4, v44, v4
	v_add_f32_e32 v3, v53, v3
	v_add_f32_e32 v2, v52, v2
	ds_write2_b32 v116, v0, v1 offset1:32
	ds_write2_b32 v116, v2, v3 offset0:64 offset1:96
	ds_write2_b32 v116, v4, v5 offset0:128 offset1:160
	ds_write2_b32 v116, v6, v7 offset0:192 offset1:224
	v_add_u32_e32 v0, 0x400, v116
	v_add_f32_e32 v22, v30, v22
	v_add_f32_e32 v15, v15, v19
	v_add_f32_e32 v14, v14, v18
	v_add_f32_e32 v13, v13, v17
	v_add_f32_e32 v12, v12, v16
	v_add_f32_e32 v11, v21, v11
	v_add_f32_e32 v10, v20, v10
	ds_write2_b32 v0, v8, v9 offset1:32
	ds_write2_b32 v0, v10, v11 offset0:64 offset1:96
	ds_write2_b32 v0, v12, v13 offset0:128 offset1:160
	ds_write2_b32 v0, v14, v15 offset0:192 offset1:224
	ds_write_b32 v116, v22 offset:2048

; __device__ __forceinline__ unsigned short bf1(float x) { return (unsigned short)(cvtpk(x, x) & 0xffffu); }
; __device__ __forceinline__ void ret_scan(Ctx& C, int nsb) {
;     ...
;         for (int c0 = 0; c0 < 128; c0 += 16) {
;             float u[4][16];
; #pragma unroll
;             for (int k = 0; k < 16; ++k)
; #pragma unroll
;                 for (int j = 0; j < 4; ++j) u[j][k] = __builtin_nontemporal_load(U + (size_t)(c0 + k) * 131072 + j * 32768 + idx0);
; #pragma unroll
;             for (int k = 0; k < 16; ++k)
; #pragma unroll
;                 for (int j = 0; j < 4; ++j) { SP[(size_t)(c0 + k) * 131072 + j * 32768 + idx0] = bf1(S[j]); S[j] = g128[j] * (S[j] + u[j][k]); }
.LBB0_997:
	v_lshl_add_u64 v[92:93], s[18:19], 0, v[20:21]
	s_mov_b64 s[98:99], 0x1358d000
	v_lshl_add_u64 v[164:165], v[92:93], 0, s[98:99]
	s_mov_b64 s[98:99], 0x20000
	global_load_dword v102, v[164:165], off offset:2304 nt
	v_lshl_add_u64 v[164:165], v[164:165], 0, s[98:99]
	global_load_dword v103, v[164:165], off offset:2304 nt
	v_lshl_add_u64 v[164:165], v[164:165], 0, s[98:99]
	global_load_dword v100, v[164:165], off offset:2304 nt
	v_lshl_add_u64 v[164:165], v[164:165], 0, s[98:99]
	global_load_dword v101, v[164:165], off offset:2304 nt
	v_lshl_add_u64 v[164:165], v[164:165], 0, s[98:99]
	global_load_dword v106, v[164:165], off offset:2304 nt
	v_lshl_add_u64 v[164:165], v[164:165], 0, s[98:99]
	global_load_dword v107, v[164:165], off offset:2304 nt
	v_lshl_add_u64 v[164:165], v[164:165], 0, s[98:99]
	global_load_dword v104, v[164:165], off offset:2304 nt
	v_lshl_add_u64 v[164:165], v[164:165], 0, s[98:99]
	global_load_dword v105, v[164:165], off offset:2304 nt
	v_lshl_add_u64 v[164:165], v[164:165], 0, s[98:99]
	global_load_dword v110, v[164:165], off offset:2304 nt
	v_lshl_add_u64 v[164:165], v[164:165], 0, s[98:99]
	global_load_dword v111, v[164:165], off offset:2304 nt
	v_lshl_add_u64 v[164:165], v[164:165], 0, s[98:99]
	global_load_dword v108, v[164:165], off offset:2304 nt
	v_lshl_add_u64 v[164:165], v[164:165], 0, s[98:99]
	global_load_dword v109, v[164:165], off offset:2304 nt
	v_lshl_add_u64 v[164:165], v[164:165], 0, s[98:99]
	global_load_dword v114, v[164:165], off offset:2304 nt
	v_lshl_add_u64 v[164:165], v[164:165], 0, s[98:99]
	global_load_dword v115, v[164:165], off offset:2304 nt
	v_lshl_add_u64 v[164:165], v[164:165], 0, s[98:99]
	global_load_dword v112, v[164:165], off offset:2304 nt
	v_lshl_add_u64 v[164:165], v[164:165], 0, s[98:99]
	global_load_dword v113, v[164:165], off offset:2304 nt
	v_lshl_add_u64 v[164:165], v[164:165], 0, s[98:99]
	global_load_dword v118, v[164:165], off offset:2304 nt
	v_lshl_add_u64 v[164:165], v[164:165], 0, s[98:99]
	global_load_dword v119, v[164:165], off offset:2304 nt
	v_lshl_add_u64 v[164:165], v[164:165], 0, s[98:99]
	global_load_dword v116, v[164:165], off offset:2304 nt
	v_lshl_add_u64 v[164:165], v[164:165], 0, s[98:99]
	global_load_dword v117, v[164:165], off offset:2304 nt
	v_lshl_add_u64 v[164:165], v[164:165], 0, s[98:99]
	global_load_dword v122, v[164:165], off offset:2304 nt
	v_lshl_add_u64 v[164:165], v[164:165], 0, s[98:99]
	global_load_dword v123, v[164:165], off offset:2304 nt
	v_lshl_add_u64 v[164:165], v[164:165], 0, s[98:99]
	global_load_dword v120, v[164:165], off offset:2304 nt
	v_lshl_add_u64 v[164:165], v[164:165], 0, s[98:99]
	global_load_dword v121, v[164:165], off offset:2304 nt
	v_lshl_add_u64 v[164:165], v[164:165], 0, s[98:99]
	global_load_dword v126, v[164:165], off offset:2304 nt
	v_lshl_add_u64 v[164:165], v[164:165], 0, s[98:99]
	global_load_dword v127, v[164:165], off offset:2304 nt
	v_lshl_add_u64 v[164:165], v[164:165], 0, s[98:99]
	global_load_dword v124, v[164:165], off offset:2304 nt
	v_lshl_add_u64 v[164:165], v[164:165], 0, s[98:99]
	global_load_dword v125, v[164:165], off offset:2304 nt
	v_lshl_add_u64 v[164:165], v[164:165], 0, s[98:99]
	global_load_dword v130, v[164:165], off offset:2304 nt
	v_lshl_add_u64 v[164:165], v[164:165], 0, s[98:99]
	global_load_dword v131, v[164:165], off offset:2304 nt
	v_lshl_add_u64 v[164:165], v[164:165], 0, s[98:99]
	global_load_dword v128, v[164:165], off offset:2304 nt
	v_lshl_add_u64 v[164:165], v[164:165], 0, s[98:99]
	global_load_dword v129, v[164:165], off offset:2304 nt
	v_lshl_add_u64 v[164:165], v[164:165], 0, s[98:99]
	global_load_dword v134, v[164:165], off offset:2304 nt
	v_lshl_add_u64 v[164:165], v[164:165], 0, s[98:99]
	global_load_dword v135, v[164:165], off offset:2304 nt
	v_lshl_add_u64 v[164:165], v[164:165], 0, s[98:99]
	global_load_dword v132, v[164:165], off offset:2304 nt
	v_lshl_add_u64 v[164:165], v[164:165], 0, s[98:99]
	global_load_dword v133, v[164:165], off offset:2304 nt
	v_lshl_add_u64 v[164:165], v[164:165], 0, s[98:99]
	global_load_dword v138, v[164:165], off offset:2304 nt
	v_lshl_add_u64 v[164:165], v[164:165], 0, s[98:99]
	global_load_dword v139, v[164:165], off offset:2304 nt
	v_lshl_add_u64 v[164:165], v[164:165], 0, s[98:99]
	global_load_dword v136, v[164:165], off offset:2304 nt
	v_lshl_add_u64 v[164:165], v[164:165], 0, s[98:99]
	global_load_dword v137, v[164:165], off offset:2304 nt
	v_lshl_add_u64 v[164:165], v[164:165], 0, s[98:99]
	global_load_dword v142, v[164:165], off offset:2304 nt
	v_lshl_add_u64 v[164:165], v[164:165], 0, s[98:99]
	global_load_dword v143, v[164:165], off offset:2304 nt
	v_lshl_add_u64 v[164:165], v[164:165], 0, s[98:99]
	global_load_dword v140, v[164:165], off offset:2304 nt
	v_lshl_add_u64 v[164:165], v[164:165], 0, s[98:99]
	global_load_dword v141, v[164:165], off offset:2304 nt
	v_lshl_add_u64 v[164:165], v[164:165], 0, s[98:99]
	global_load_dword v146, v[164:165], off offset:2304 nt
	v_lshl_add_u64 v[164:165], v[164:165], 0, s[98:99]
	global_load_dword v147, v[164:165], off offset:2304 nt
	v_lshl_add_u64 v[164:165], v[164:165], 0, s[98:99]
	global_load_dword v144, v[164:165], off offset:2304 nt
	v_lshl_add_u64 v[164:165], v[164:165], 0, s[98:99]
	global_load_dword v145, v[164:165], off offset:2304 nt
	v_lshl_add_u64 v[164:165], v[164:165], 0, s[98:99]
	global_load_dword v150, v[164:165], off offset:2304 nt
	v_lshl_add_u64 v[164:165], v[164:165], 0, s[98:99]
	global_load_dword v151, v[164:165], off offset:2304 nt
	v_lshl_add_u64 v[164:165], v[164:165], 0, s[98:99]
	global_load_dword v148, v[164:165], off offset:2304 nt
; __device__ __forceinline__ unsigned short bf1(float x) { return (unsigned short)(cvtpk(x, x) & 0xffffu); }
; __device__ __forceinline__ void ret_scan(Ctx& C, int nsb) {
;     ...
;         for (int c0 = 0; c0 < 128; c0 += 16) {
;             float u[4][16];
; #pragma unroll
;             for (int k = 0; k < 16; ++k)
; #pragma unroll
;                 for (int j = 0; j < 4; ++j) u[j][k] = __builtin_nontemporal_load(U + (size_t)(c0 + k) * 131072 + j * 32768 + idx0);
; #pragma unroll
;             for (int k = 0; k < 16; ++k)
; #pragma unroll
;                 for (int j = 0; j < 4; ++j) { SP[(size_t)(c0 + k) * 131072 + j * 32768 + idx0] = bf1(S[j]); S[j] = g128[j] * (S[j] + u[j][k]); }
	v_lshl_add_u64 v[164:165], v[164:165], 0, s[98:99]
	global_load_dword v149, v[164:165], off offset:2304 nt
	v_lshl_add_u64 v[164:165], v[164:165], 0, s[98:99]
	global_load_dword v154, v[164:165], off offset:2304 nt
	v_lshl_add_u64 v[164:165], v[164:165], 0, s[98:99]
	global_load_dword v155, v[164:165], off offset:2304 nt
	v_lshl_add_u64 v[164:165], v[164:165], 0, s[98:99]
	global_load_dword v152, v[164:165], off offset:2304 nt
	v_lshl_add_u64 v[164:165], v[164:165], 0, s[98:99]
	global_load_dword v153, v[164:165], off offset:2304 nt
	v_lshl_add_u64 v[164:165], v[164:165], 0, s[98:99]
	global_load_dword v158, v[164:165], off offset:2304 nt
	v_lshl_add_u64 v[164:165], v[164:165], 0, s[98:99]
	global_load_dword v159, v[164:165], off offset:2304 nt
	v_lshl_add_u64 v[164:165], v[164:165], 0, s[98:99]
	global_load_dword v156, v[164:165], off offset:2304 nt
	v_lshl_add_u64 v[164:165], v[164:165], 0, s[98:99]
	global_load_dword v157, v[164:165], off offset:2304 nt
	v_lshl_add_u64 v[164:165], v[164:165], 0, s[98:99]
	global_load_dword v162, v[164:165], off offset:2304 nt
	v_lshl_add_u64 v[164:165], v[164:165], 0, s[98:99]
	global_load_dword v163, v[164:165], off offset:2304 nt
	v_lshl_add_u64 v[164:165], v[164:165], 0, s[98:99]
	global_load_dword v160, v[164:165], off offset:2304 nt
	v_lshl_add_u64 v[164:165], v[164:165], 0, s[98:99]
	global_load_dword v161, v[164:165], off offset:2304 nt
	v_add_co_u32_e32 v28, vcc, 0x1358d000, v92
	v_cvt_pk_bf16_f32 v95, v95, v95
	v_cvt_pk_bf16_f32 v14, v14, v14
	v_cvt_pk_bf16_f32 v1, v1, v1
	s_mov_b32 s0, 0x175ed000
	s_nop 0
	v_addc_co_u32_e32 v29, vcc, 0, v93, vcc
	v_add_co_u32_e32 v28, vcc, 0x135ad000, v92
	s_add_i32 s82, s82, 16
	s_nop 0
	v_addc_co_u32_e32 v29, vcc, 0, v93, vcc
	v_add_co_u32_e32 v28, vcc, 0x135cd000, v92
	v_lshl_add_u64 v[20:21], v[20:21], 0, s[26:27]
	s_nop 0
	v_addc_co_u32_e32 v29, vcc, 0, v93, vcc
	v_add_co_u32_e32 v28, vcc, 0x135ed000, v92
	s_cmpk_gt_u32 s82, 0x6f
	s_nop 0
	v_addc_co_u32_e32 v29, vcc, 0, v93, vcc
	v_add_co_u32_e32 v28, vcc, 0x1360d000, v92
	s_waitcnt vmcnt(60) lgkmcnt(0)
	v_pk_add_f32 v[24:25], v[24:25], v[102:103]
	v_addc_co_u32_e32 v29, vcc, 0, v93, vcc
	v_add_co_u32_e32 v28, vcc, 0x1362d000, v92
	v_pk_mul_f32 v[76:77], v[16:17], v[24:25]
	s_nop 0
	v_addc_co_u32_e32 v29, vcc, 0, v93, vcc
	v_add_co_u32_e32 v28, vcc, 0x1364d000, v92
	v_pk_add_f32 v[26:27], v[26:27], v[100:101]
	s_nop 0
	v_addc_co_u32_e32 v29, vcc, 0, v93, vcc
	v_add_co_u32_e32 v28, vcc, 0x1366d000, v92
	v_pk_mul_f32 v[74:75], v[18:19], v[26:27]
	s_nop 0
	v_addc_co_u32_e32 v29, vcc, 0, v93, vcc
	v_add_co_u32_e32 v28, vcc, 0x1368d000, v92
	s_waitcnt vmcnt(56) lgkmcnt(0)
	v_pk_fma_f32 v[24:25], v[16:17], v[24:25], v[106:107]
	v_addc_co_u32_e32 v29, vcc, 0, v93, vcc
	v_add_co_u32_e32 v28, vcc, 0x136ad000, v92
	v_pk_fma_f32 v[26:27], v[18:19], v[26:27], v[104:105]
	s_nop 0
	v_addc_co_u32_e32 v29, vcc, 0, v93, vcc
	v_add_co_u32_e32 v28, vcc, 0x136cd000, v92
	v_pk_mul_f32 v[78:79], v[18:19], v[26:27]
	s_nop 0
	v_addc_co_u32_e32 v29, vcc, 0, v93, vcc
	v_add_co_u32_e32 v28, vcc, 0x136ed000, v92
	s_nop 1
	v_addc_co_u32_e32 v29, vcc, 0, v93, vcc
	v_add_co_u32_e32 v28, vcc, 0x1370d000, v92
	s_waitcnt vmcnt(52) lgkmcnt(0)
	v_pk_fma_f32 v[26:27], v[18:19], v[26:27], v[108:109]
	v_addc_co_u32_e32 v29, vcc, 0, v93, vcc
	v_add_co_u32_e32 v28, vcc, 0x1372d000, v92
	v_pk_mul_f32 v[82:83], v[18:19], v[26:27]
	s_nop 0
	v_addc_co_u32_e32 v29, vcc, 0, v93, vcc
	v_add_co_u32_e32 v28, vcc, 0x1374d000, v92
	s_nop 1
	v_addc_co_u32_e32 v29, vcc, 0, v93, vcc
	v_add_co_u32_e32 v28, vcc, 0x1376d000, v92
	s_nop 1
	v_addc_co_u32_e32 v29, vcc, 0, v93, vcc
	v_add_co_u32_e32 v28, vcc, 0x1378d000, v92
	s_waitcnt vmcnt(48) lgkmcnt(0)
	v_pk_fma_f32 v[26:27], v[18:19], v[26:27], v[112:113]
	v_addc_co_u32_e32 v29, vcc, 0, v93, vcc
	v_add_co_u32_e32 v28, vcc, 0x137ad000, v92
	v_pk_mul_f32 v[86:87], v[18:19], v[26:27]
	s_nop 0
	v_addc_co_u32_e32 v29, vcc, 0, v93, vcc
	v_add_co_u32_e32 v28, vcc, 0x137cd000, v92
	s_nop 1
	v_addc_co_u32_e32 v29, vcc, 0, v93, vcc
	v_add_co_u32_e32 v28, vcc, 0x137ed000, v92
	s_nop 1
	v_addc_co_u32_e32 v29, vcc, 0, v93, vcc
	v_add_co_u32_e32 v28, vcc, 0x1380d000, v92
	s_waitcnt vmcnt(44) lgkmcnt(0)
	v_pk_fma_f32 v[26:27], v[18:19], v[26:27], v[116:117]
	v_addc_co_u32_e32 v29, vcc, 0, v93, vcc
	v_add_co_u32_e32 v28, vcc, 0x1382d000, v92
	v_pk_mul_f32 v[50:51], v[18:19], v[26:27]
	s_nop 0
	v_addc_co_u32_e32 v29, vcc, 0, v93, vcc
	v_add_co_u32_e32 v28, vcc, 0x1384d000, v92
	s_nop 1
	v_addc_co_u32_e32 v29, vcc, 0, v93, vcc
	v_add_co_u32_e32 v28, vcc, 0x1386d000, v92
	s_nop 1
	v_addc_co_u32_e32 v29, vcc, 0, v93, vcc
	v_add_co_u32_e32 v28, vcc, 0x1388d000, v92
	s_waitcnt vmcnt(40) lgkmcnt(0)
	v_pk_fma_f32 v[26:27], v[18:19], v[26:27], v[120:121]
	v_addc_co_u32_e32 v29, vcc, 0, v93, vcc
	v_add_co_u32_e32 v28, vcc, 0x138ad000, v92
	v_pk_mul_f32 v[36:37], v[18:19], v[26:27]
	s_nop 0
	v_addc_co_u32_e32 v29, vcc, 0, v93, vcc
	v_add_co_u32_e32 v28, vcc, 0x138cd000, v92
	s_nop 1
	v_addc_co_u32_e32 v29, vcc, 0, v93, vcc
	v_add_co_u32_e32 v28, vcc, 0x138ed000, v92
	s_nop 1
	v_addc_co_u32_e32 v29, vcc, 0, v93, vcc
	v_add_co_u32_e32 v28, vcc, 0x1390d000, v92
	s_waitcnt vmcnt(36) lgkmcnt(0)
	v_pk_fma_f32 v[26:27], v[18:19], v[26:27], v[124:125]
	v_addc_co_u32_e32 v29, vcc, 0, v93, vcc
	v_add_co_u32_e32 v28, vcc, 0x1392d000, v92
	v_pk_mul_f32 v[44:45], v[18:19], v[26:27]
	s_nop 0
	v_addc_co_u32_e32 v29, vcc, 0, v93, vcc
	v_add_co_u32_e32 v28, vcc, 0x1394d000, v92
	s_nop 1
	v_addc_co_u32_e32 v29, vcc, 0, v93, vcc
	v_add_co_u32_e32 v28, vcc, 0x1396d000, v92
	s_nop 1
	v_addc_co_u32_e32 v29, vcc, 0, v93, vcc
	v_add_co_u32_e32 v28, vcc, 0x1398d000, v92
	s_waitcnt vmcnt(32) lgkmcnt(0)
; __device__ __forceinline__ unsigned short bf1(float x) { return (unsigned short)(cvtpk(x, x) & 0xffffu); }
; __device__ __forceinline__ void ret_scan(Ctx& C, int nsb) {
;     ...
;         for (int c0 = 0; c0 < 128; c0 += 16) {
;             float u[4][16];
; #pragma unroll
;             for (int k = 0; k < 16; ++k)
; #pragma unroll
;                 for (int j = 0; j < 4; ++j) u[j][k] = __builtin_nontemporal_load(U + (size_t)(c0 + k) * 131072 + j * 32768 + idx0);
; #pragma unroll
;             for (int k = 0; k < 16; ++k)
; #pragma unroll
;                 for (int j = 0; j < 4; ++j) { SP[(size_t)(c0 + k) * 131072 + j * 32768 + idx0] = bf1(S[j]); S[j] = g128[j] * (S[j] + u[j][k]); }
	v_pk_fma_f32 v[26:27], v[18:19], v[26:27], v[128:129]
	v_addc_co_u32_e32 v29, vcc, 0, v93, vcc
	v_add_co_u32_e32 v28, vcc, 0x139ad000, v92
	v_pk_mul_f32 v[54:55], v[18:19], v[26:27]
	s_nop 0
	v_addc_co_u32_e32 v29, vcc, 0, v93, vcc
	v_add_co_u32_e32 v28, vcc, 0x139cd000, v92
	s_nop 1
	v_addc_co_u32_e32 v29, vcc, 0, v93, vcc
	v_add_co_u32_e32 v28, vcc, 0x139ed000, v92
	s_nop 1
	v_addc_co_u32_e32 v29, vcc, 0, v93, vcc
	v_add_co_u32_e32 v28, vcc, 0x13a0d000, v92
	s_waitcnt vmcnt(28) lgkmcnt(0)
	v_pk_fma_f32 v[26:27], v[18:19], v[26:27], v[132:133]
	v_addc_co_u32_e32 v29, vcc, 0, v93, vcc
	v_add_co_u32_e32 v28, vcc, 0x13a2d000, v92
	v_pk_mul_f32 v[62:63], v[18:19], v[26:27]
	s_nop 0
	v_addc_co_u32_e32 v29, vcc, 0, v93, vcc
	v_add_co_u32_e32 v28, vcc, 0x13a4d000, v92
	s_nop 1
	v_addc_co_u32_e32 v29, vcc, 0, v93, vcc
	v_add_co_u32_e32 v28, vcc, 0x13a6d000, v92
	s_nop 1
	v_addc_co_u32_e32 v29, vcc, 0, v93, vcc
	v_add_co_u32_e32 v28, vcc, 0x13a8d000, v92
	s_waitcnt vmcnt(24) lgkmcnt(0)
	v_pk_fma_f32 v[26:27], v[18:19], v[26:27], v[136:137]
	v_addc_co_u32_e32 v29, vcc, 0, v93, vcc
	v_add_co_u32_e32 v28, vcc, 0x13aad000, v92
	s_nop 1
	v_addc_co_u32_e32 v29, vcc, 0, v93, vcc
	v_add_co_u32_e32 v28, vcc, 0x13acd000, v92
	s_nop 1
	v_addc_co_u32_e32 v29, vcc, 0, v93, vcc
	v_add_co_u32_e32 v28, vcc, 0x13aed000, v92
	s_nop 1
	v_addc_co_u32_e32 v29, vcc, 0, v93, vcc
	v_add_co_u32_e32 v28, vcc, 0x13b0d000, v92
	s_nop 1
	v_addc_co_u32_e32 v29, vcc, 0, v93, vcc
	v_add_co_u32_e32 v28, vcc, 0x13b2d000, v92
	s_nop 1
	v_addc_co_u32_e32 v29, vcc, 0, v93, vcc
	v_add_co_u32_e32 v28, vcc, 0x13b4d000, v92
	s_nop 1
	v_addc_co_u32_e32 v29, vcc, 0, v93, vcc
	v_add_co_u32_e32 v28, vcc, 0x13b6d000, v92
	s_nop 1
	v_addc_co_u32_e32 v29, vcc, 0, v93, vcc
	v_add_co_u32_e32 v28, vcc, 0x13b8d000, v92
	s_nop 1
	v_addc_co_u32_e32 v29, vcc, 0, v93, vcc
	v_add_co_u32_e32 v28, vcc, 0x13bad000, v92
	s_nop 1
	v_addc_co_u32_e32 v29, vcc, 0, v93, vcc
	v_add_co_u32_e32 v28, vcc, 0x13bcd000, v92
	s_nop 1
	v_addc_co_u32_e32 v29, vcc, 0, v93, vcc
	v_add_co_u32_e32 v28, vcc, 0x13bed000, v92
	s_nop 1
	v_addc_co_u32_e32 v29, vcc, 0, v93, vcc
	v_add_co_u32_e32 v28, vcc, 0x13c0d000, v92
	s_nop 1
	v_addc_co_u32_e32 v29, vcc, 0, v93, vcc
	v_add_co_u32_e32 v28, vcc, 0x13c2d000, v92
	s_nop 1
	v_addc_co_u32_e32 v29, vcc, 0, v93, vcc
	v_add_co_u32_e32 v28, vcc, 0x13c4d000, v92
	s_nop 1
	v_addc_co_u32_e32 v29, vcc, 0, v93, vcc
	v_add_co_u32_e32 v28, vcc, 0x13c6d000, v92
	s_nop 1
	v_addc_co_u32_e32 v29, vcc, 0, v93, vcc
	v_add_co_u32_e32 v28, vcc, 0x13c8d000, v92
	s_nop 1
	v_addc_co_u32_e32 v29, vcc, 0, v93, vcc
	v_add_co_u32_e32 v28, vcc, 0x13cad000, v92
	s_nop 1
	v_addc_co_u32_e32 v29, vcc, 0, v93, vcc
	v_add_co_u32_e32 v28, vcc, 0x13ccd000, v92
	s_nop 1
	v_addc_co_u32_e32 v29, vcc, 0, v93, vcc
	v_add_co_u32_e32 v28, vcc, 0x13ced000, v92
	s_nop 1
	v_addc_co_u32_e32 v29, vcc, 0, v93, vcc
	v_add_co_u32_e32 v28, vcc, 0x13d0d000, v92
	s_nop 1
	v_addc_co_u32_e32 v29, vcc, 0, v93, vcc
	v_add_co_u32_e32 v28, vcc, 0x13d2d000, v92
	s_nop 1
	v_addc_co_u32_e32 v29, vcc, 0, v93, vcc
	v_add_co_u32_e32 v28, vcc, 0x13d4d000, v92
	s_nop 1
	v_addc_co_u32_e32 v29, vcc, 0, v93, vcc
	v_add_co_u32_e32 v92, vcc, 0x13d6d000, v92
	s_nop 0
	v_addc_co_u32_e32 v93, vcc, 0, v93, vcc
	v_lshl_add_u64 v[92:93], s[18:19], 0, v[22:23]
	v_add_co_u32_e32 v96, vcc, 0x1758d000, v92
	v_lshl_add_u64 v[22:23], v[22:23], 0, s[24:25]
	s_nop 0
	v_addc_co_u32_e32 v97, vcc, 0, v93, vcc
	global_store_short v[96:97], v95, off offset:2304
	v_cvt_pk_bf16_f32 v96, v94, v94
	v_add_co_u32_e32 v94, vcc, 0x1759d000, v92
	s_nop 1
	v_addc_co_u32_e32 v95, vcc, 0, v93, vcc
	global_store_short v[94:95], v96, off offset:2304
	v_add_co_u32_e32 v94, vcc, 0x175ad000, v92
	s_nop 1
	v_addc_co_u32_e32 v95, vcc, 0, v93, vcc
	global_store_short v[94:95], v14, off offset:2304
	v_add_co_u32_e32 v94, vcc, 0x175bd000, v92
	s_nop 1
	v_addc_co_u32_e32 v95, vcc, 0, v93, vcc
	global_store_short v[94:95], v1, off offset:2304
	v_add_co_u32_e32 v94, vcc, 0x175cd000, v92
	v_cvt_pk_bf16_f32 v1, v76, v76
	s_nop 1
	v_addc_co_u32_e32 v95, vcc, 0, v93, vcc
	v_add_co_u32_e32 v76, vcc, 0x175dd000, v92
	global_store_short v[94:95], v1, off offset:2304
	v_cvt_pk_bf16_f32 v1, v77, v77
	s_nop 0
	v_addc_co_u32_e32 v77, vcc, 0, v93, vcc
	global_store_short v[76:77], v1, off offset:2304
	v_pk_mul_f32 v[76:77], v[16:17], v[24:25]
	v_pk_fma_f32 v[24:25], v[16:17], v[24:25], v[110:111]
	v_cvt_pk_bf16_f32 v1, v74, v74
	s_nop 0
	v_pk_mul_f32 v[80:81], v[16:17], v[24:25]
	v_pk_fma_f32 v[24:25], v[16:17], v[24:25], v[114:115]
	s_nop 0
	v_pk_mul_f32 v[84:85], v[16:17], v[24:25]
	v_pk_fma_f32 v[24:25], v[16:17], v[24:25], v[118:119]
	v_add_co_u32_e32 v90, vcc, s0, v92
	s_mov_b32 s0, 0x175fd000
	s_nop 0
	v_addc_co_u32_e32 v91, vcc, 0, v93, vcc
	v_add_co_u32_e32 v74, vcc, s0, v92
	global_store_short v[90:91], v1, off offset:2304
	v_cvt_pk_bf16_f32 v1, v75, v75
	s_nop 0
	v_addc_co_u32_e32 v75, vcc, 0, v93, vcc
	s_mov_b32 s0, 0x1760d000
	global_store_short v[74:75], v1, off offset:2304
	v_add_co_u32_e32 v74, vcc, s0, v92
	s_mov_b32 s0, 0x1761d000
	s_nop 0
	v_addc_co_u32_e32 v75, vcc, 0, v93, vcc
	v_cvt_pk_bf16_f32 v1, v76, v76
	global_store_short v[74:75], v1, off offset:2304
	v_add_co_u32_e32 v74, vcc, s0, v92
	s_mov_b32 s0, 0x1762d000
	s_nop 0
	v_addc_co_u32_e32 v75, vcc, 0, v93, vcc
	v_cvt_pk_bf16_f32 v1, v77, v77
	global_store_short v[74:75], v1, off offset:2304
	v_add_co_u32_e32 v74, vcc, s0, v92
	s_mov_b32 s0, 0x1763d000
	s_nop 0
	v_addc_co_u32_e32 v75, vcc, 0, v93, vcc
	v_cvt_pk_bf16_f32 v1, v78, v78
	global_store_short v[74:75], v1, off offset:2304
	v_add_co_u32_e32 v74, vcc, s0, v92
; __device__ __forceinline__ unsigned short bf1(float x) { return (unsigned short)(cvtpk(x, x) & 0xffffu); }
; __device__ __forceinline__ void ret_scan(Ctx& C, int nsb) {
;     ...
;         for (int c0 = 0; c0 < 128; c0 += 16) {
;             float u[4][16];
; #pragma unroll
;             for (int k = 0; k < 16; ++k)
; #pragma unroll
;                 for (int j = 0; j < 4; ++j) u[j][k] = __builtin_nontemporal_load(U + (size_t)(c0 + k) * 131072 + j * 32768 + idx0);
; #pragma unroll
;             for (int k = 0; k < 16; ++k)
; #pragma unroll
;                 for (int j = 0; j < 4; ++j) { SP[(size_t)(c0 + k) * 131072 + j * 32768 + idx0] = bf1(S[j]); S[j] = g128[j] * (S[j] + u[j][k]); }
	s_mov_b32 s0, 0x1764d000
	s_nop 0
	v_addc_co_u32_e32 v75, vcc, 0, v93, vcc
	v_cvt_pk_bf16_f32 v1, v79, v79
	global_store_short v[74:75], v1, off offset:2304
	v_add_co_u32_e32 v74, vcc, s0, v92
	s_mov_b32 s0, 0x1765d000
	s_nop 0
	v_addc_co_u32_e32 v75, vcc, 0, v93, vcc
	v_cvt_pk_bf16_f32 v1, v80, v80
	global_store_short v[74:75], v1, off offset:2304
	v_add_co_u32_e32 v74, vcc, s0, v92
	v_cvt_pk_bf16_f32 v1, v81, v81
	v_pk_mul_f32 v[88:89], v[16:17], v[24:25]
	s_nop 0
	v_addc_co_u32_e32 v75, vcc, 0, v93, vcc
	global_store_short v[74:75], v1, off offset:2304
	v_add_co_u32_e32 v74, vcc, s1, v92
	v_cvt_pk_bf16_f32 v1, v82, v82
	v_pk_fma_f32 v[24:25], v[16:17], v[24:25], v[122:123]
	s_nop 0
	v_addc_co_u32_e32 v75, vcc, 0, v93, vcc
	global_store_short v[74:75], v1, off offset:2304
	v_add_co_u32_e32 v74, vcc, s7, v92
	v_cvt_pk_bf16_f32 v1, v83, v83
	v_pk_mul_f32 v[42:43], v[16:17], v[24:25]
	s_nop 0
	v_addc_co_u32_e32 v75, vcc, 0, v93, vcc
	global_store_short v[74:75], v1, off offset:2304
	v_add_co_u32_e32 v74, vcc, s28, v92
	v_cvt_pk_bf16_f32 v1, v84, v84
	v_pk_fma_f32 v[24:25], v[16:17], v[24:25], v[126:127]
	s_nop 0
	v_addc_co_u32_e32 v75, vcc, 0, v93, vcc
	global_store_short v[74:75], v1, off offset:2304
	v_add_co_u32_e32 v74, vcc, s29, v92
	v_cvt_pk_bf16_f32 v1, v85, v85
	s_nop 1
	v_addc_co_u32_e32 v75, vcc, 0, v93, vcc
	global_store_short v[74:75], v1, off offset:2304
	v_add_co_u32_e32 v74, vcc, s30, v92
	v_cvt_pk_bf16_f32 v1, v86, v86
	s_nop 1
	v_addc_co_u32_e32 v75, vcc, 0, v93, vcc
	global_store_short v[74:75], v1, off offset:2304
	v_add_co_u32_e32 v74, vcc, s31, v92
	v_cvt_pk_bf16_f32 v1, v87, v87
	s_nop 1
	v_addc_co_u32_e32 v75, vcc, 0, v93, vcc
	global_store_short v[74:75], v1, off offset:2304
	v_add_co_u32_e32 v74, vcc, s34, v92
	v_cvt_pk_bf16_f32 v1, v88, v88
	s_nop 1
	v_addc_co_u32_e32 v75, vcc, 0, v93, vcc
	global_store_short v[74:75], v1, off offset:2304
	v_add_co_u32_e32 v74, vcc, s35, v92
	v_cvt_pk_bf16_f32 v1, v89, v89
	s_nop 1
	v_addc_co_u32_e32 v75, vcc, 0, v93, vcc
	global_store_short v[74:75], v1, off offset:2304
	v_add_co_u32_e32 v74, vcc, s36, v92
	v_cvt_pk_bf16_f32 v1, v50, v50
	s_nop 1
	v_addc_co_u32_e32 v75, vcc, 0, v93, vcc
	v_add_co_u32_e32 v50, vcc, s37, v92
	global_store_short v[74:75], v1, off offset:2304
	v_cvt_pk_bf16_f32 v1, v51, v51
	s_nop 0
	v_addc_co_u32_e32 v51, vcc, 0, v93, vcc
	global_store_short v[50:51], v1, off offset:2304
	v_add_co_u32_e32 v50, vcc, s38, v92
	v_cvt_pk_bf16_f32 v1, v42, v42
	s_nop 1
	v_addc_co_u32_e32 v51, vcc, 0, v93, vcc
	v_add_co_u32_e32 v42, vcc, s39, v92
	global_store_short v[50:51], v1, off offset:2304
	v_cvt_pk_bf16_f32 v1, v43, v43
	s_nop 0
	v_addc_co_u32_e32 v43, vcc, 0, v93, vcc
	v_add_co_u32_e32 v68, vcc, s40, v92
	global_store_short v[42:43], v1, off offset:2304
	s_nop 0
	v_addc_co_u32_e32 v69, vcc, 0, v93, vcc
	v_cvt_pk_bf16_f32 v1, v36, v36
	v_add_co_u32_e32 v36, vcc, s41, v92
	global_store_short v[68:69], v1, off offset:2304
	v_cvt_pk_bf16_f32 v1, v37, v37
	s_nop 0
	v_addc_co_u32_e32 v37, vcc, 0, v93, vcc
	global_store_short v[36:37], v1, off offset:2304
	v_add_co_u32_e32 v36, vcc, s42, v92
	v_pk_mul_f32 v[42:43], v[16:17], v[24:25]
	s_nop 0
	v_addc_co_u32_e32 v37, vcc, 0, v93, vcc
	v_cvt_pk_bf16_f32 v1, v42, v42
	global_store_short v[36:37], v1, off offset:2304
	v_add_co_u32_e32 v36, vcc, s43, v92
	v_cvt_pk_bf16_f32 v1, v43, v43
	v_pk_fma_f32 v[24:25], v[16:17], v[24:25], v[130:131]
	s_nop 0
	v_addc_co_u32_e32 v37, vcc, 0, v93, vcc
	global_store_short v[36:37], v1, off offset:2304
	v_add_co_u32_e32 v36, vcc, s44, v92
	v_cvt_pk_bf16_f32 v1, v44, v44
	v_pk_mul_f32 v[46:47], v[16:17], v[24:25]
	s_nop 0
	v_addc_co_u32_e32 v37, vcc, 0, v93, vcc
	global_store_short v[36:37], v1, off offset:2304
	v_add_co_u32_e32 v36, vcc, s45, v92
	v_cvt_pk_bf16_f32 v1, v45, v45
	v_pk_fma_f32 v[24:25], v[16:17], v[24:25], v[134:135]
	s_nop 0
	v_addc_co_u32_e32 v37, vcc, 0, v93, vcc
	global_store_short v[36:37], v1, off offset:2304
	v_add_co_u32_e32 v36, vcc, s46, v92
	v_cvt_pk_bf16_f32 v1, v46, v46
	v_pk_mul_f32 v[50:51], v[16:17], v[24:25]
	s_nop 0
	v_addc_co_u32_e32 v37, vcc, 0, v93, vcc
	global_store_short v[36:37], v1, off offset:2304
	v_add_co_u32_e32 v36, vcc, s47, v92
	v_cvt_pk_bf16_f32 v1, v47, v47
	v_pk_fma_f32 v[24:25], v[16:17], v[24:25], v[138:139]
	s_nop 0
	v_addc_co_u32_e32 v37, vcc, 0, v93, vcc
	global_store_short v[36:37], v1, off offset:2304
	v_add_co_u32_e32 v36, vcc, s48, v92
	v_cvt_pk_bf16_f32 v1, v54, v54
	v_pk_mul_f32 v[56:57], v[16:17], v[24:25]
	s_nop 0
	v_addc_co_u32_e32 v37, vcc, 0, v93, vcc
	global_store_short v[36:37], v1, off offset:2304
	v_add_co_u32_e32 v36, vcc, s49, v92
	v_cvt_pk_bf16_f32 v1, v55, v55
	v_pk_mul_f32 v[64:65], v[18:19], v[26:27]
	s_nop 0
	v_addc_co_u32_e32 v37, vcc, 0, v93, vcc
	global_store_short v[36:37], v1, off offset:2304
	v_add_co_u32_e32 v36, vcc, s50, v92
	v_cvt_pk_bf16_f32 v1, v50, v50
	s_waitcnt vmcnt(36) lgkmcnt(0)
; __device__ __forceinline__ unsigned short bf1(float x) { return (unsigned short)(cvtpk(x, x) & 0xffffu); }
; __device__ __forceinline__ void ret_scan(Ctx& C, int nsb) {
;     ...
;         for (int c0 = 0; c0 < 128; c0 += 16) {
;             float u[4][16];
; #pragma unroll
;             for (int k = 0; k < 16; ++k)
; #pragma unroll
;                 for (int j = 0; j < 4; ++j) u[j][k] = __builtin_nontemporal_load(U + (size_t)(c0 + k) * 131072 + j * 32768 + idx0);
; #pragma unroll
;             for (int k = 0; k < 16; ++k)
; #pragma unroll
;                 for (int j = 0; j < 4; ++j) { SP[(size_t)(c0 + k) * 131072 + j * 32768 + idx0] = bf1(S[j]); S[j] = g128[j] * (S[j] + u[j][k]); }
;         }
; #pragma unroll
;         for (int j = 0; j < 4; ++j) C.out[O_STP + ((size_t)j * 128 + d) * 256 + e] = S[j];
;     }
	v_pk_fma_f32 v[24:25], v[16:17], v[24:25], v[142:143]
	v_addc_co_u32_e32 v37, vcc, 0, v93, vcc
	global_store_short v[36:37], v1, off offset:2304
	v_add_co_u32_e32 v36, vcc, s51, v92
	v_cvt_pk_bf16_f32 v1, v51, v51
	v_pk_fma_f32 v[26:27], v[18:19], v[26:27], v[140:141]
	s_nop 0
	v_addc_co_u32_e32 v37, vcc, 0, v93, vcc
	global_store_short v[36:37], v1, off offset:2304
	v_add_co_u32_e32 v36, vcc, s52, v92
	v_cvt_pk_bf16_f32 v1, v62, v62
	v_pk_mul_f32 v[34:35], v[16:17], v[24:25]
	s_nop 0
	v_addc_co_u32_e32 v37, vcc, 0, v93, vcc
	global_store_short v[36:37], v1, off offset:2304
	v_add_co_u32_e32 v36, vcc, s53, v92
	v_cvt_pk_bf16_f32 v1, v63, v63
	v_pk_mul_f32 v[42:43], v[18:19], v[26:27]
	s_nop 0
	v_addc_co_u32_e32 v37, vcc, 0, v93, vcc
	global_store_short v[36:37], v1, off offset:2304
	v_add_co_u32_e32 v36, vcc, s54, v92
	v_cvt_pk_bf16_f32 v1, v56, v56
	v_pk_fma_f32 v[26:27], v[18:19], v[26:27], v[144:145]
	s_nop 0
	v_addc_co_u32_e32 v37, vcc, 0, v93, vcc
	global_store_short v[36:37], v1, off offset:2304
	v_add_co_u32_e32 v36, vcc, s55, v92
	v_cvt_pk_bf16_f32 v1, v57, v57
	v_pk_mul_f32 v[30:31], v[18:19], v[26:27]
	s_nop 0
	v_addc_co_u32_e32 v37, vcc, 0, v93, vcc
	global_store_short v[36:37], v1, off offset:2304
	v_add_co_u32_e32 v36, vcc, s56, v92
	v_cvt_pk_bf16_f32 v1, v64, v64
	v_pk_fma_f32 v[26:27], v[18:19], v[26:27], v[148:149]
	s_nop 0
	v_addc_co_u32_e32 v37, vcc, 0, v93, vcc
	global_store_short v[36:37], v1, off offset:2304
	v_add_co_u32_e32 v36, vcc, s57, v92
	v_cvt_pk_bf16_f32 v1, v65, v65
	v_pk_mul_f32 v[38:39], v[18:19], v[26:27]
	s_nop 0
	v_addc_co_u32_e32 v37, vcc, 0, v93, vcc
	global_store_short v[36:37], v1, off offset:2304
	v_add_co_u32_e32 v36, vcc, s58, v92
	v_cvt_pk_bf16_f32 v1, v34, v34
	v_pk_fma_f32 v[26:27], v[18:19], v[26:27], v[152:153]
	s_nop 0
	v_addc_co_u32_e32 v37, vcc, 0, v93, vcc
	v_add_co_u32_e32 v34, vcc, s59, v92
	global_store_short v[36:37], v1, off offset:2304
	v_cvt_pk_bf16_f32 v1, v35, v35
	s_nop 0
	v_addc_co_u32_e32 v35, vcc, 0, v93, vcc
	v_add_co_u32_e32 v48, vcc, s61, v92
	global_store_short v[34:35], v1, off offset:2304
	s_nop 0
	v_addc_co_u32_e32 v49, vcc, 0, v93, vcc
	v_cvt_pk_bf16_f32 v1, v42, v42
	v_add_co_u32_e32 v42, vcc, s62, v92
	global_store_short v[48:49], v1, off offset:2304
	v_cvt_pk_bf16_f32 v1, v43, v43
	s_nop 0
	v_addc_co_u32_e32 v43, vcc, 0, v93, vcc
	v_pk_fma_f32 v[24:25], v[16:17], v[24:25], v[146:147]
	global_store_short v[42:43], v1, off offset:2304
	v_add_co_u32_e32 v42, vcc, s63, v92
	v_pk_mul_f32 v[32:33], v[16:17], v[24:25]
	s_nop 0
	v_addc_co_u32_e32 v43, vcc, 0, v93, vcc
	v_cvt_pk_bf16_f32 v1, v32, v32
	v_add_co_u32_e32 v32, vcc, s65, v92
	global_store_short v[42:43], v1, off offset:2304
	v_cvt_pk_bf16_f32 v1, v33, v33
	s_nop 0
	v_addc_co_u32_e32 v33, vcc, 0, v93, vcc
	global_store_short v[32:33], v1, off offset:2304
	v_add_co_u32_e32 v32, vcc, s66, v92
	v_cvt_pk_bf16_f32 v1, v30, v30
	v_pk_fma_f32 v[24:25], v[16:17], v[24:25], v[150:151]
	s_nop 0
	v_addc_co_u32_e32 v33, vcc, 0, v93, vcc
	v_add_co_u32_e32 v30, vcc, s67, v92
	global_store_short v[32:33], v1, off offset:2304
	v_cvt_pk_bf16_f32 v1, v31, v31
	s_nop 0
	v_addc_co_u32_e32 v31, vcc, 0, v93, vcc
	global_store_short v[30:31], v1, off offset:2304
	v_add_co_u32_e32 v30, vcc, s68, v92
	v_pk_mul_f32 v[34:35], v[16:17], v[24:25]
	s_nop 0
	v_addc_co_u32_e32 v31, vcc, 0, v93, vcc
	v_cvt_pk_bf16_f32 v1, v34, v34
	global_store_short v[30:31], v1, off offset:2304
	v_add_co_u32_e32 v30, vcc, s69, v92
	v_cvt_pk_bf16_f32 v1, v35, v35
	v_pk_fma_f32 v[24:25], v[16:17], v[24:25], v[154:155]
	s_nop 0
	v_addc_co_u32_e32 v31, vcc, 0, v93, vcc
	global_store_short v[30:31], v1, off offset:2304
	v_add_co_u32_e32 v30, vcc, s70, v92
	v_cvt_pk_bf16_f32 v1, v38, v38
	v_pk_mul_f32 v[36:37], v[16:17], v[24:25]
	s_nop 0
	v_addc_co_u32_e32 v31, vcc, 0, v93, vcc
	global_store_short v[30:31], v1, off offset:2304
	v_add_co_u32_e32 v30, vcc, s71, v92
	v_cvt_pk_bf16_f32 v1, v39, v39
	v_pk_mul_f32 v[44:45], v[18:19], v[26:27]
	s_nop 0
	v_addc_co_u32_e32 v31, vcc, 0, v93, vcc
	global_store_short v[30:31], v1, off offset:2304
	v_add_co_u32_e32 v30, vcc, s72, v92
	v_cvt_pk_bf16_f32 v1, v36, v36
	v_pk_fma_f32 v[24:25], v[16:17], v[24:25], v[158:159]
	s_nop 0
	v_addc_co_u32_e32 v31, vcc, 0, v93, vcc
	global_store_short v[30:31], v1, off offset:2304
	v_add_co_u32_e32 v30, vcc, s73, v92
	v_cvt_pk_bf16_f32 v1, v37, v37
	v_pk_mul_f32 v[40:41], v[16:17], v[24:25]
	s_nop 0
	v_addc_co_u32_e32 v31, vcc, 0, v93, vcc
	global_store_short v[30:31], v1, off offset:2304
	v_add_co_u32_e32 v30, vcc, s74, v92
	v_cvt_pk_bf16_f32 v1, v44, v44
	v_pk_fma_f32 v[26:27], v[18:19], v[26:27], v[156:157]
	s_nop 0
	v_addc_co_u32_e32 v31, vcc, 0, v93, vcc
	global_store_short v[30:31], v1, off offset:2304
	v_add_co_u32_e32 v30, vcc, s75, v92
	v_cvt_pk_bf16_f32 v1, v45, v45
	v_pk_fma_f32 v[24:25], v[16:17], v[24:25], v[162:163]
	s_nop 0
	v_addc_co_u32_e32 v31, vcc, 0, v93, vcc
	global_store_short v[30:31], v1, off offset:2304
	v_add_co_u32_e32 v30, vcc, s76, v92
	v_cvt_pk_bf16_f32 v1, v40, v40
	v_pk_mul_f32 v[46:47], v[18:19], v[26:27]
	s_nop 0
	v_addc_co_u32_e32 v31, vcc, 0, v93, vcc
	global_store_short v[30:31], v1, off offset:2304
	v_add_co_u32_e32 v30, vcc, s77, v92
	v_cvt_pk_bf16_f32 v1, v41, v41
	v_pk_fma_f32 v[26:27], v[18:19], v[26:27], v[160:161]
	s_nop 0
	v_addc_co_u32_e32 v31, vcc, 0, v93, vcc
	global_store_short v[30:31], v1, off offset:2304
	v_add_co_u32_e32 v30, vcc, s79, v92
	v_cvt_pk_bf16_f32 v1, v46, v46
	v_pk_mul_f32 v[24:25], v[16:17], v[24:25]
	s_nop 0
	v_addc_co_u32_e32 v31, vcc, 0, v93, vcc
	v_add_co_u32_e32 v28, vcc, s80, v92
	global_store_short v[30:31], v1, off offset:2304
	v_pk_mul_f32 v[26:27], v[18:19], v[26:27]
	v_cvt_pk_bf16_f32 v1, v47, v47
	v_addc_co_u32_e32 v29, vcc, 0, v93, vcc
	global_store_short v[28:29], v1, off offset:2304
	v_mov_b32_e32 v95, v24
	v_mov_b32_e32 v94, v25
	v_mov_b32_e32 v14, v26
	v_mov_b32_e32 v1, v27
	s_cbranch_scc0 .LBB0_997
	v_lshlrev_b32_e32 v1, 10, v0
	v_and_b32_e32 v14, 0x1fc00, v1
	v_lshrrev_b32_e32 v1, 5, v0
	v_lshl_add_u64 v[16:17], s[16:17], 0, v[14:15]
	v_and_b32_e32 v14, 0x3fc, v1
	v_lshl_add_u64 v[16:17], v[16:17], 0, v[14:15]
	v_add_co_u32_e32 v18, vcc, 0x60a0000, v16
	v_add_u32_e32 v0, s6, v0
	s_nop 0
	v_addc_co_u32_e32 v19, vcc, 0, v17, vcc
	global_store_dword v[18:19], v24, off
	v_add_co_u32_e32 v18, vcc, 0x60c0000, v16
	v_lshl_add_u64 v[2:3], v[2:3], 0, s[10:11]
	s_nop 0
	v_addc_co_u32_e32 v19, vcc, 0, v17, vcc
	global_store_dword v[18:19], v25, off
	v_add_co_u32_e32 v18, vcc, 0x60e0000, v16
	v_lshl_add_u64 v[4:5], v[4:5], 0, s[20:21]
	s_nop 0
	v_addc_co_u32_e32 v19, vcc, 0, v17, vcc
	v_add_co_u32_e32 v16, vcc, 0x6100000, v16
	global_store_dword v[18:19], v26, off
	s_nop 0
	v_addc_co_u32_e32 v17, vcc, 0, v17, vcc
	v_cmp_lt_i32_e32 vcc, s81, v0
	s_or_b64 s[22:23], vcc, s[22:23]
	global_store_dword v[16:17], v27, off
	s_andn2_b64 exec, exec, s[22:23]
	s_cbranch_execnz .LBB0_996

; __device__ __forceinline__ unsigned cvtpk(float lo, float hi) { unsigned r; asm("v_cvt_pk_bf16_f32 %0, %1, %2" : "=v"(r) : "v"(lo), "v"(hi)); return r; }
; __device__ __forceinline__ float col_total(float l) { l += __shfl_xor(l, 16); l += __shfl_xor(l, 32); return l; }
; __device__ __forceinline__ void nsa_block_task(Ctx& C, int task, bf16* ONSA_OUT) {
;     ...
; #pragma unroll
;         for (int cg = 0; cg < 2; ++cg) { const float lt = col_total(a[cg].l); const float sc = lt > 0.f ? g_w[cg] / lt : 0.f;
;         bf16* od = ONSA_OUT + (size_t)tl[cg] * 512 + head * 64 + 4 * fq;
; #pragma unroll
;             for (int c = 0; c < 4; ++c) { const f4 ov = STASH[(cg * 4 + c) * 64 + lane] + a[cg].o[c] * sc;
;                 v2u wv; wv.x = cvtpk(ov[0], ov[1]); wv.y = cvtpk(ov[2], ov[3]); *(v2u*)(od + 16 * c) = wv; } }
.LBB0_1111:
	global_load_dwordx4 v[88:91], v[200:201], off
	global_load_dwordx4 v[92:95], v[200:201], off offset:1024
	global_load_dwordx4 v[96:99], v[200:201], off offset:2048
	global_load_dwordx4 v[100:103], v[200:201], off offset:3072
	global_load_dwordx4 v[104:107], v[202:203], off
	global_load_dwordx4 v[108:111], v[204:205], off
	global_load_dwordx4 v[112:115], v[206:207], off
	global_load_dwordx4 v[116:119], v[208:209], off
	ds_bpermute_b32 v0, v217, v68
	s_waitcnt lgkmcnt(0)
	v_add_f32_e32 v8, v68, v0
	ds_bpermute_b32 v9, v219, v8
	v_lshlrev_b32_e32 v0, 1, v220
	v_lshl_add_u64 v[6:7], v[210:211], 0, v[0:1]
	s_waitcnt lgkmcnt(0)
	v_add_f32_e32 v0, v8, v9
	v_div_scale_f32 v10, s[16:17], v0, v0, v188
	v_rcp_f32_e32 v11, v10
	v_div_scale_f32 v12, vcc, v188, v0, v188
	v_lshl_add_u64 v[8:9], v[6:7], 0, v[214:215]
	v_fma_f32 v13, -v10, v11, 1.0
	v_fmac_f32_e32 v11, v13, v11
	v_mul_f32_e32 v13, v12, v11
	v_fma_f32 v14, -v10, v13, v12
	v_fmac_f32_e32 v13, v14, v11
	v_fma_f32 v10, -v10, v13, v12
	v_div_fmas_f32 v10, v10, v11, v13
	v_div_fixup_f32 v10, v10, v0, v188
	v_cmp_lt_f32_e32 vcc, 0, v0
	v_lshl_add_u64 v[6:7], v[6:7], 0, v[212:213]
	s_nop 0
	v_cndmask_b32_e32 v0, 0, v10, vcc
	s_waitcnt vmcnt(0)
	v_pk_fma_f32 v[2:3], v[80:81], v[0:1], v[88:89] op_sel_hi:[1,0,1]
	v_pk_fma_f32 v[4:5], v[82:83], v[0:1], v[90:91] op_sel_hi:[1,0,1]
	v_cvt_pk_bf16_f32 v2, v2, v3
	s_nop 0
	v_cvt_pk_bf16_f32 v3, v4, v5
	global_store_dwordx2 v[8:9], v[2:3], off
	s_waitcnt lgkmcnt(0)
	v_pk_fma_f32 v[2:3], v[76:77], v[0:1], v[92:93] op_sel_hi:[1,0,1]
	v_pk_fma_f32 v[4:5], v[78:79], v[0:1], v[94:95] op_sel_hi:[1,0,1]
	v_cvt_pk_bf16_f32 v2, v2, v3
	s_nop 0
	v_cvt_pk_bf16_f32 v3, v4, v5
	global_store_dwordx2 v[8:9], v[2:3], off offset:32
	s_waitcnt lgkmcnt(0)
	v_pk_fma_f32 v[2:3], v[72:73], v[0:1], v[96:97] op_sel_hi:[1,0,1]
	v_pk_fma_f32 v[4:5], v[74:75], v[0:1], v[98:99] op_sel_hi:[1,0,1]
	v_cvt_pk_bf16_f32 v2, v2, v3
	s_nop 0
	v_cvt_pk_bf16_f32 v3, v4, v5
	global_store_dwordx2 v[8:9], v[2:3], off offset:64
	s_waitcnt lgkmcnt(0)
	v_pk_fma_f32 v[2:3], v[84:85], v[0:1], v[100:101] op_sel_hi:[1,0,1]
	v_pk_fma_f32 v[4:5], v[86:87], v[0:1], v[102:103] op_sel_hi:[1,0,1]
	v_cvt_pk_bf16_f32 v2, v2, v3
	ds_bpermute_b32 v0, v217, v238
	v_cvt_pk_bf16_f32 v3, v4, v5
	global_store_dwordx2 v[8:9], v[2:3], off offset:96
	s_waitcnt lgkmcnt(0)
	v_add_f32_e32 v0, v238, v0
	ds_bpermute_b32 v8, v219, v0
	s_waitcnt lgkmcnt(0)
	v_add_f32_e32 v0, v0, v8
	v_div_scale_f32 v8, s[16:17], v0, v0, v184
	v_rcp_f32_e32 v9, v8
	v_div_scale_f32 v10, vcc, v184, v0, v184
	s_mov_b64 s[16:17], 0
	v_fma_f32 v11, -v8, v9, 1.0
	v_fmac_f32_e32 v9, v11, v9
	v_mul_f32_e32 v11, v10, v9
	v_fma_f32 v12, -v8, v11, v10
	v_fmac_f32_e32 v11, v12, v9
	v_fma_f32 v8, -v8, v11, v10
	v_div_fmas_f32 v8, v8, v9, v11
	v_div_fixup_f32 v8, v8, v0, v184
	v_cmp_lt_f32_e32 vcc, 0, v0
	s_nop 1
	v_cndmask_b32_e32 v0, 0, v8, vcc
	v_pk_fma_f32 v[2:3], v[176:177], v[0:1], v[104:105] op_sel_hi:[1,0,1]
	v_pk_fma_f32 v[4:5], v[178:179], v[0:1], v[106:107] op_sel_hi:[1,0,1]
	v_cvt_pk_bf16_f32 v2, v2, v3
	s_nop 0
	v_cvt_pk_bf16_f32 v3, v4, v5
	global_store_dwordx2 v[6:7], v[2:3], off
	s_waitcnt lgkmcnt(0)
	v_pk_fma_f32 v[2:3], v[172:173], v[0:1], v[108:109] op_sel_hi:[1,0,1]
	v_pk_fma_f32 v[4:5], v[174:175], v[0:1], v[110:111] op_sel_hi:[1,0,1]
	v_cvt_pk_bf16_f32 v2, v2, v3
	s_nop 0
	v_cvt_pk_bf16_f32 v3, v4, v5
	global_store_dwordx2 v[6:7], v[2:3], off offset:32
	s_waitcnt lgkmcnt(0)
	v_pk_fma_f32 v[2:3], v[168:169], v[0:1], v[112:113] op_sel_hi:[1,0,1]
	v_pk_fma_f32 v[4:5], v[170:171], v[0:1], v[114:115] op_sel_hi:[1,0,1]
	v_cvt_pk_bf16_f32 v2, v2, v3
	s_nop 0
	v_cvt_pk_bf16_f32 v3, v4, v5
	global_store_dwordx2 v[6:7], v[2:3], off offset:64
	s_waitcnt lgkmcnt(0)
	v_pk_fma_f32 v[2:3], v[180:181], v[0:1], v[116:117] op_sel_hi:[1,0,1]
	v_pk_fma_f32 v[4:5], v[182:183], v[0:1], v[118:119] op_sel_hi:[1,0,1]
	v_cvt_pk_bf16_f32 v2, v2, v3
	s_nop 0
	v_cvt_pk_bf16_f32 v3, v4, v5
	global_store_dwordx2 v[6:7], v[2:3], off offset:96
	s_waitcnt lgkmcnt(0)
	s_barrier

; __device__ __forceinline__ unsigned xb_add(unsigned* p, unsigned v) { return __hip_atomic_fetch_add(p, v, __ATOMIC_RELAXED, __HIP_MEMORY_SCOPE_AGENT); }
; __global__ void __launch_bounds__(NWAVES * 64, 2) hybrid_fwd(Args args) {
;     ...
;         for (;;) {
;             if (C.tid == 0) MISC[16] = xb_add(ctl + 320, 1u);
;             __syncthreads();
;             const unsigned qi = MISC[16];
;             __syncthreads();
;             if (qi >= 512u) break;
;             const int qbn = 255 - (int)(qi >> 1);
;             nsa_block_task(C, (qi & 1u) ? 511 - qbn : qbn, WSP(bf16, WS_ONSA));
.LBB0_1113:
	s_and_saveexec_b64 s[16:17], s[4:5]
	s_cbranch_execz .LBB0_1115
	s_waitcnt vmcnt(0)
	v_readlane_b32 s98, v255, 6
	s_and_b32 s98, s98, 7
	s_lshl_b32 s98, s98, 8
	s_add_i32 s98, s98, 0x800
	s_mov_b32 s99, 0
	v_lshl_add_u64 v[2:3], v[194:195], 0, s[98:99]
	global_atomic_add v0, v[2:3], v228, off sc0
	v_mov_b32_e32 v2, s89
	v_readlane_b32 s98, v255, 6
	s_and_b32 s98, s98, 7
	s_waitcnt vmcnt(0) lgkmcnt(0)
	v_lshlrev_b32_e32 v0, 3, v0
	v_or_b32_e32 v0, s98, v0
	ds_write_b32 v2, v0

; #define LAS __attribute__((address_space(3)))
; __device__ __forceinline__ int launder_v(int x) { asm volatile("" : "+v"(x)); return x; }
; template <int STG, class F>
; __device__ __forceinline__ void stream_tiles(Ctx& C, const TileSrc& src, int tile0, int ntiles, LAS unsigned char* bufs, F&& compute) {
;     if (ntiles <= 0) return;
;     const int nst = (ntiles + STG - 1) / STG, tlast = tile0 + ntiles - 1;
;     v4u rk[STG], rv[STG];
;     { const int tidl = launder_v(C.tid);
; #pragma unroll
;       for (int h = 0; h < STG; ++h) { const int t = tile0 + h; tile_fetch(src, 64 * (t < tlast ? t : tlast), tidl, rk[h], rv[h]); }
; #pragma unroll
;       for (int h = 0; h < STG; ++h) tile_store(bufs + h * 16384, tidl, rk[h], rv[h]); }
;     __syncthreads();
; __device__ __forceinline__ void nsa_block_task(Ctx& C, int task, bf16* ONSA_OUT) {
;     ...
; #pragma unroll
;         for (int cg = 0; cg < 2; ++cg)
; #pragma unroll
;             for (int c = 0; c < 4; ++c) oc[cg][c] = o[cg][c] * g_c[cg];
;     }
;     WAVE_SYNC();
;     {
; #pragma unroll 1
;         for (int q = 0; q < 8; ++q) {
;             if (qb < 16) { if (lane < 8) SELM[q * 8 + lane] = (lane == 0) ? ((1u << (qb + 1)) - 1u) : 0u; }
;             else select_blocks(SC + q * 256, SELM + q * 8, qb - 2, qb, qb - 1, lane);
;         }
;     }
;     WAVE_SYNC();
;     LAS unsigned* ANYM = (LAS unsigned*)(C.lds + 135168 + w * 64);
;     { const int la = launder_v(lane); if (la < 16) { const int cgx = la >> 3, w8 = la & 7; ANYM[la] = SELM[(4 * cgx + 0) * 8 + w8] | SELM[(4 * cgx + 1) * 8 + w8] | SELM[(4 * cgx + 2) * 8 + w8] | SELM[(4 * cgx + 3) * 8 + w8]; } }
;     WAVE_SYNC();
;     f4* STASH = WSP(f4, WS_STASH) + (size_t)(C.bid * NWAVES + w) * 512;
; #pragma unroll
;     for (int cg = 0; cg < 2; ++cg)
; #pragma unroll
;         for (int c = 0; c < 4; ++c) STASH[(cg * 4 + c) * 64 + lane] = oc[cg][c];
;     __syncthreads();
;     {
;         AttnAcc a[2]; attn_init(a[0]); attn_init(a[1]);
;         const int kvs = launder_s(kvh);
;         const TileSrc src{WSP(bf16, WS_KS) + (size_t)kvs * RP * 64, WSP(bf16, WS_VST) + (size_t)kvs * 64 * RP, RP};
;         int cw = -1; unsigned aw0 = 0u, aw1 = 0u;
;         stream_tiles<4>(C, src, 0, qb, bufs, [&](const LAS unsigned char* buf, int j) {
.LBB0_1206:
	s_or_b64 exec, exec, s[16:17]
	v_pk_mul_f32 v[32:33], v[186:187], v[32:33] op_sel_hi:[0,1]
	v_pk_mul_f32 v[34:35], v[186:187], v[34:35] op_sel_hi:[0,1]
	s_mov_b32 s3, s97
	v_pk_mul_f32 v[48:49], v[186:187], v[48:49] op_sel_hi:[0,1]
	v_pk_mul_f32 v[50:51], v[186:187], v[50:51] op_sel_hi:[0,1]
	v_pk_mul_f32 v[44:45], v[186:187], v[44:45] op_sel_hi:[0,1]
	v_pk_mul_f32 v[46:47], v[186:187], v[46:47] op_sel_hi:[0,1]
	v_pk_mul_f32 v[36:37], v[182:183], v[36:37] op_sel_hi:[0,1]
	v_pk_mul_f32 v[38:39], v[182:183], v[38:39] op_sel_hi:[0,1]
	v_pk_mul_f32 v[40:41], v[182:183], v[40:41] op_sel_hi:[0,1]
	v_pk_mul_f32 v[42:43], v[182:183], v[42:43] op_sel_hi:[0,1]
	v_pk_mul_f32 v[28:29], v[186:187], v[28:29] op_sel_hi:[0,1]
	v_pk_mul_f32 v[30:31], v[186:187], v[30:31] op_sel_hi:[0,1]
	v_pk_mul_f32 v[20:21], v[182:183], v[20:21] op_sel_hi:[0,1]
	v_pk_mul_f32 v[22:23], v[182:183], v[22:23] op_sel_hi:[0,1]
	v_pk_mul_f32 v[24:25], v[182:183], v[24:25] op_sel_hi:[0,1]
	v_pk_mul_f32 v[26:27], v[182:183], v[26:27] op_sel_hi:[0,1]
	s_waitcnt lgkmcnt(0)
	global_store_dwordx4 v[200:201], v[32:35], off
	global_store_dwordx4 v[200:201], v[48:51], off offset:1024
	global_store_dwordx4 v[200:201], v[28:31], off offset:2048
	global_store_dwordx4 v[200:201], v[44:47], off offset:3072
	global_store_dwordx4 v[202:203], v[20:23], off
	global_store_dwordx4 v[204:205], v[36:39], off
	global_store_dwordx4 v[206:207], v[24:27], off
	global_store_dwordx4 v[208:209], v[40:43], off
	s_waitcnt lgkmcnt(0)
	s_barrier
	s_mul_hi_i32 s17, s3, 0x208000
	s_mul_i32 s3, s3, 0x208000
	s_add_u32 s18, s79, s3
	s_addc_u32 s19, s80, s17
	s_add_u32 s16, s81, s3
	s_addc_u32 s17, s82, s17
	s_cmp_eq_u32 s94, 0
	s_mov_b32 s26, 0
	s_cbranch_scc1 .LBB0_1229
	v_mov_b32_e32 v36, v189
	s_add_i32 s3, s94, 3
	v_ashrrev_i32_e32 v20, 3, v36
	v_lshlrev_b32_e32 v28, 4, v36
	v_and_b32_e32 v0, 0x70, v28
	v_ashrrev_i32_e32 v21, 31, v20
	v_mov_b64_e32 v[22:23], s[16:17]
	v_lshl_add_u64 v[2:3], s[18:19], 0, v[0:1]
	v_mad_i64_i32 v[22:23], s[20:21], v20, s92, v[22:23]
	v_lshlrev_b64 v[24:25], 7, v[20:21]
	s_cmp_eq_u32 s0, 0
	v_lshl_add_u64 v[24:25], v[2:3], 0, v[24:25]
	s_cselect_b32 s20, 0, 64
	v_lshl_add_u64 v[22:23], v[22:23], 0, v[0:1]
	global_load_dwordx4 v[56:59], v[24:25], off
	global_load_dwordx4 v[60:63], v[22:23], off
	v_add_u32_e32 v24, s20, v20
	v_ashrrev_i32_e32 v25, 31, v24
	v_lshlrev_b64 v[24:25], 7, v[24:25]
	v_lshl_add_u64 v[24:25], v[2:3], 0, v[24:25]
	s_lshl_b32 s50, s20, 1
	s_min_u32 s20, s0, 2
	v_lshl_add_u64 v[26:27], v[22:23], 0, s[50:51]
	global_load_dwordx4 v[64:67], v[24:25], off
	global_load_dwordx4 v[68:71], v[26:27], off
	v_lshl_add_u32 v24, s20, 6, v20
	v_ashrrev_i32_e32 v25, 31, v24
	v_lshlrev_b64 v[24:25], 7, v[24:25]
	v_lshl_add_u64 v[24:25], v[2:3], 0, v[24:25]
	s_lshl_b32 s50, s20, 7
	s_min_u32 s20, s0, 3
	v_lshl_add_u64 v[26:27], v[22:23], 0, s[50:51]
	global_load_dwordx4 v[72:75], v[24:25], off
	global_load_dwordx4 v[76:79], v[26:27], off
	v_lshl_add_u32 v24, s20, 6, v20
	v_ashrrev_i32_e32 v25, 31, v24
	v_lshlrev_b64 v[24:25], 7, v[24:25]
	v_lshl_add_u64 v[2:3], v[2:3], 0, v[24:25]
	s_lshl_b32 s50, s20, 7
	v_lshl_add_u64 v[22:23], v[22:23], 0, s[50:51]
	global_load_dwordx4 v[80:83], v[2:3], off
	global_load_dwordx4 v[84:87], v[22:23], off
	v_lshlrev_b32_e32 v0, 2, v20
	v_lshrrev_b32_e32 v21, 1, v20
	v_mov_b32_e32 v2, v1
	v_mov_b32_e32 v3, v1
	v_and_b32_e32 v22, 35, v20
	v_lshlrev_b32_e32 v20, 7, v20
	v_bitop3_b32 v23, v28, s91, v36 bitop3:0x48
	v_and_b32_e32 v24, 16, v0
	v_and_b32_e32 v21, 12, v21
	v_add3_u32 v37, 0, v20, v23
	v_mov_b32_e32 v0, v1
	v_or3_b32 v38, v24, v22, v21
	v_mov_b64_e32 v[22:23], v[2:3]
	v_mov_b64_e32 v[26:27], v[2:3]
	v_mov_b64_e32 v[30:31], v[2:3]
	v_mov_b64_e32 v[34:35], v[2:3]
	v_mov_b64_e32 v[42:43], v[2:3]
	v_mov_b64_e32 v[46:47], v[2:3]
	v_mov_b64_e32 v[50:51], v[2:3]
	v_mov_b64_e32 v[54:55], v[2:3]
	v_mov_b64_e32 v[20:21], v[0:1]
	v_mov_b64_e32 v[24:25], v[0:1]
	v_mov_b64_e32 v[28:29], v[0:1]
	v_mov_b64_e32 v[32:33], v[0:1]
	v_mov_b64_e32 v[40:41], v[0:1]
	v_mov_b64_e32 v[44:45], v[0:1]
	v_mov_b64_e32 v[48:49], v[0:1]
	v_mov_b64_e32 v[52:53], v[0:1]
	v_lshrrev_b32_e32 v2, 1, v38
	v_xor_b32_e32 v2, v2, v36
	v_lshlrev_b32_e32 v2, 4, v2
	v_lshlrev_b32_e32 v0, 7, v38
	v_and_b32_e32 v2, 0x70, v2
	s_mov_b32 s27, 0
	v_mov_b32_e32 v169, 0xc4800000
	v_mov_b32_e32 v168, 0
	s_mov_b32 s22, -1
	s_mov_b32 s28, 0
	s_mov_b32 s31, 0
	s_mov_b32 s30, 0
	s_lshr_b32 s29, s3, 2
	v_add3_u32 v0, 0, v0, v2
	v_mov_b32_e32 v36, 0
	v_mov_b32_e32 v170, 0xc4800000
	s_mov_b32 s23, 0
	s_waitcnt vmcnt(0) lgkmcnt(0)
	ds_write_b128 v0, v[56:59]
	ds_write_b128 v37, v[60:63] offset:8192
	ds_write_b128 v0, v[64:67] offset:16384
	ds_write_b128 v37, v[68:71] offset:24576
	ds_write_b128 v0, v[72:75] offset:32768
	ds_write_b128 v37, v[76:79] offset:40960
	ds_write_b128 v0, v[80:83] offset:49152
	ds_write_b128 v37, v[84:87] offset:57344
	s_waitcnt lgkmcnt(0)
	s_barrier

; __device__ __forceinline__ bf16x8 pack8(const f4& a, const f4& b) { return __builtin_bit_cast(bf16x8, pack8u(a, b)); }
; __device__ __forceinline__ float fexp2(float x) { return __builtin_amdgcn_exp2f(x); }
; #define MFMA16(a, b, c) __builtin_amdgcn_mfma_f32_16x16x32_bf16((a), (b), (c), 0, 0, 0)
;     ...
;     float ps = 0.f; bf16x8 pb[2];
; #pragma unroll
;     for (int ch = 0; ch < 2; ++ch) { f4 p0, p1;
; #pragma unroll
;         for (int j = 0; j < 4; ++j) { p0[j] = fexp2(s[ch][0][j] - a.m); p1[j] = fexp2(s[ch][1][j] - a.m); ps += p0[j] + p1[j]; }
;         pb[ch] = pack8(p0, p1); }
;     a.l += ps;
; #pragma unroll
;     for (int ch = 0; ch < 2; ++ch)
; #pragma unroll
;         for (int c = 0; c < 4; ++c) a.o[c] = MFMA16(vf[ch][c], pb[ch], a.o[c]);
.LBB0_1211:
	v_exp_f32_e32 v136, v140
	v_exp_f32_e32 v137, v144
	v_exp_f32_e32 v2, v141
	v_exp_f32_e32 v0, v145
	v_add_f32_e32 v3, v136, v137
	v_pk_add_f32 v[124:125], v[2:3], v[0:1]
	s_nop 0
	v_pk_add_f32 v[132:133], v[124:125], v[124:125] op_sel_hi:[0,1]
	v_exp_f32_e32 v138, v146
	v_exp_f32_e32 v3, v142
	v_exp_f32_e32 v126, v143
	v_exp_f32_e32 v132, v147
	v_add_f32_e32 v127, v3, v138
	v_pk_add_f32 v[124:125], v[126:127], v[132:133]
	s_nop 0
	v_pk_add_f32 v[134:135], v[124:125], v[124:125] op_sel_hi:[0,1]
	v_cvt_pk_bf16_f32 v124, v136, v2
	v_exp_f32_e32 v128, v128
	v_cvt_pk_bf16_f32 v125, v3, v126
	v_exp_f32_e32 v133, v120
	v_exp_f32_e32 v2, v129
	v_exp_f32_e32 v134, v121
	v_add_f32_e32 v3, v128, v133
	v_cvt_pk_bf16_f32 v126, v137, v0
	v_pk_add_f32 v[120:121], v[2:3], v[134:135]
	v_cvt_pk_bf16_f32 v127, v138, v132
	v_pk_add_f32 v[120:121], v[120:121], v[120:121] op_sel_hi:[0,1]
	s_nop 0
	v_mfma_f32_16x16x32_bf16 v[32:35], v[116:119], v[124:127], v[32:35]
	v_exp_f32_e32 v0, v130
	v_exp_f32_e32 v3, v122
	v_mfma_f32_16x16x32_bf16 v[28:31], v[112:115], v[124:127], v[28:31]
	v_exp_f32_e32 v112, v131
	v_add_f32_e32 v113, v0, v3
	v_mfma_f32_16x16x32_bf16 v[24:27], v[108:111], v[124:127], v[24:27]
	v_exp_f32_e32 v120, v123
	v_cvt_pk_bf16_f32 v108, v128, v2
	v_mfma_f32_16x16x32_bf16 v[20:23], v[104:107], v[124:127], v[20:23]
	v_cvt_pk_bf16_f32 v109, v0, v112
	v_cvt_pk_bf16_f32 v110, v133, v134
	v_cvt_pk_bf16_f32 v111, v3, v120
	v_add_f32_e64 v2, v112, v120
	v_add_f32_e64 v3, v113, v121
	v_mfma_f32_16x16x32_bf16 v[32:35], v[96:99], v[108:111], v[32:35]
	v_add_f32_e32 v0, v2, v3
	v_add_f32_e32 v168, v168, v0
	v_mfma_f32_16x16x32_bf16 v[28:31], v[100:103], v[108:111], v[28:31]
	v_mfma_f32_16x16x32_bf16 v[24:27], v[92:95], v[108:111], v[24:27]
	v_mfma_f32_16x16x32_bf16 v[20:23], v[88:91], v[108:111], v[20:23]

; __device__ __forceinline__ float fexp2(float x) { return __builtin_amdgcn_exp2f(x); }
; __device__ __forceinline__ int launder_v(int x) { asm volatile("" : "+v"(x)); return x; }
; #define MFMA16(a, b, c) __builtin_amdgcn_mfma_f32_16x16x32_bf16((a), (b), (c), 0, 0, 0)
;     f4 s[2][2];
; #pragma unroll
;     for (int ch = 0; ch < 2; ++ch)
; #pragma unroll
;         for (int kt = 0; kt < 2; ++kt) { f4 t = (f4){colbias, colbias, colbias, colbias}; t = MFMA16(kf[ch][kt][0], bq[0], t); s[ch][kt] = MFMA16(kf[ch][kt][1], bq[1], t); }
;     float mx = -1e30f;
; #pragma unroll
;     for (int ch = 0; ch < 2; ++ch)
; #pragma unroll
;         for (int h = 0; h < 2; ++h) mx = fmaxf(mx, fmaxf(fmaxf(s[ch][h][0], s[ch][h][1]), fmaxf(s[ch][h][2], s[ch][h][3])));
;     if (__any(mx > a.m + MAX_SLACK)) {
;         mx = fmaxf(mx, __shfl_xor(mx, 16)); mx = fmaxf(mx, __shfl_xor(mx, 32));
;         const float mn = fmaxf(a.m, mx), alpha = fexp2(a.m - mn); a.m = mn; a.l *= alpha;
; #pragma unroll
;         for (int c = 0; c < 4; ++c) a.o[c] = a.o[c] * alpha;
;     }
; __device__ __forceinline__ void nsa_block_task(Ctx& C, int task, bf16* ONSA_OUT) {
;     ...
;             if ((j >> 5) != cw) { cw = j >> 5; aw0 = (unsigned)__builtin_amdgcn_readfirstlane((int)ANYM[cw]); aw1 = (unsigned)__builtin_amdgcn_readfirstlane((int)ANYM[8 + cw]); }
;             bool any[2]; any[0] = (aw0 >> (j & 31)) & 1u; any[1] = (aw1 >> (j & 31)) & 1u;
;             if (any[0] || any[1]) {
;                 bool mysel[2];
; #pragma unroll
;                 for (int cg = 0; cg < 2; ++cg) mysel[cg] = (SELM[(4 * cg + qi) * 8 + (j >> 5)] >> (j & 31)) & 1u;
;                 bf16x8 kf[2][2][2], vf[2][4]; { const int ll = launder_v(lane);
; #pragma unroll
;                     for (int ch = 0; ch < 2; ++ch) { tile_read_k(buf, ch, ll, kf[ch]); tile_read_v(buf, ch, ll, vf[ch]); } }
; #pragma unroll
;                 for (int cg = 0; cg < 2; ++cg) if (any[cg]) attn_tile64_full(a[cg], kf, vf, bq[cg], mysel[cg] ? 0.f : -3e30f);
.LBB0_1217:
	s_add_i32 s40, s35, s39
	s_lshl_b32 s3, 1, s40
	s_and_b32 s22, s30, s3
	s_and_b32 s3, s31, s3
	s_or_b32 s41, s22, s3
	s_cmp_lg_u32 s22, 0
	s_cselect_b64 s[24:25], -1, 0
	s_cmp_lg_u32 s3, 0
	s_cselect_b64 s[22:23], -1, 0
	s_cmp_lg_u32 s41, 0
	s_cselect_b64 s[42:43], -1, 0
	s_andn2_b64 vcc, exec, s[42:43]
	s_cbranch_vccnz .LBB0_1212
	v_mov_b32_e32 v0, v190
	s_waitcnt lgkmcnt(0)
	ds_read2_b32 v[2:3], v171 offset1:32
	s_andn2_b64 vcc, exec, s[24:25]
	v_ashrrev_i32_e32 v88, 4, v0
	v_lshrrev_b32_e32 v89, 1, v0
	v_bitop3_b32 v90, v89, v88, 7 bitop3:0x6c
	v_lshlrev_b32_e32 v0, 7, v0
	v_add_u32_e32 v88, 4, v88
	v_lshlrev_b32_e32 v90, 4, v90
	v_and_b32_e32 v0, 0x780, v0
	v_bitop3_b32 v88, v88, v89, 7 bitop3:0x78
	v_lshlrev_b32_e32 v88, 4, v88
	v_add3_u32 v89, v0, v90, s36
	v_add3_u32 v0, v0, v88, s36
	ds_read_b128 v[140:143], v89
	ds_read_b128 v[144:147], v89 offset:2048
	ds_read_b128 v[148:151], v0
	ds_read_b128 v[128:131], v0 offset:2048
	ds_read_b128 v[116:119], v89 offset:8192
	ds_read_b128 v[112:115], v89 offset:10240
	ds_read_b128 v[108:111], v89 offset:12288
	ds_read_b128 v[104:107], v89 offset:14336
	ds_read_b128 v[136:139], v89 offset:4096
	ds_read_b128 v[124:127], v89 offset:6144
	ds_read_b128 v[132:135], v0 offset:4096
	ds_read_b128 v[120:123], v0 offset:6144
	ds_read_b128 v[96:99], v0 offset:8192
	ds_read_b128 v[100:103], v0 offset:10240
	ds_read_b128 v[92:95], v0 offset:12288
	ds_read_b128 v[88:91], v0 offset:14336
	s_cbranch_vccnz .LBB0_1222
	s_waitcnt lgkmcnt(0)
	v_lshrrev_b32_e32 v0, s40, v2
	v_and_b32_e32 v0, 1, v0
	v_cmp_eq_u32_e32 vcc, 1, v0
	s_nop 1
	v_cndmask_b32_e64 v156, v231, 0, vcc
	v_sub_f32_e32 v156, v156, v170
	v_mov_b32_e32 v157, v156
	v_mov_b32_e32 v158, v156
	v_mov_b32_e32 v159, v156
	s_nop 1
	v_mfma_f32_16x16x32_bf16 v[152:155], v[140:143], v[4:7], v[156:159]
	v_mfma_f32_16x16x32_bf16 v[160:163], v[148:151], v[8:11], v[152:155]
	v_mfma_f32_16x16x32_bf16 v[152:155], v[144:147], v[4:7], v[156:159]
	v_mfma_f32_16x16x32_bf16 v[164:167], v[128:131], v[8:11], v[152:155]
	s_nop 5
	v_max_f32_e32 v0, v163, v163
	v_max_f32_e32 v2, v162, v162
	v_max_f32_e32 v0, v2, v0
	v_mfma_f32_16x16x32_bf16 v[152:155], v[136:139], v[4:7], v[156:159]
	v_max3_f32 v0, v160, v161, v0
	v_max_f32_e32 v2, v167, v167
	v_max_f32_e32 v172, v166, v166
	v_mfma_f32_16x16x32_bf16 v[156:159], v[124:127], v[4:7], v[156:159]
	v_max_f32_e32 v2, v172, v2
	v_max3_f32 v2, v164, v165, v2
	v_max3_f32 v0, v0, s93, v2
	v_mfma_f32_16x16x32_bf16 v[152:155], v[132:135], v[8:11], v[152:155]
	v_mfma_f32_16x16x32_bf16 v[156:159], v[120:123], v[8:11], v[156:159]
	s_nop 6
	v_max_f32_e32 v2, v155, v155
	v_max_f32_e32 v172, v154, v154
	v_max_f32_e32 v2, v172, v2
	v_max_f32_e32 v172, v159, v159
	v_max_f32_e32 v173, v158, v158
	v_max_f32_e32 v172, v173, v172
	v_max3_f32 v2, v152, v153, v2
	v_max3_f32 v172, v156, v157, v172
	v_max3_f32 v0, v0, v2, v172
	v_cmp_lt_f32_e32 vcc, 0x41000000, v0
	s_cbranch_vccz .LBB0_1221
	ds_bpermute_b32 v2, v217, v0
	v_max_f32_e32 v0, v0, v0
	s_waitcnt lgkmcnt(0)
	v_max_f32_e32 v2, v2, v2
	v_max_f32_e32 v0, v0, v2
	ds_bpermute_b32 v2, v219, v0
	s_waitcnt lgkmcnt(0)
	v_max3_f32 v2, 0, v0, v2
	v_sub_f32_e32 v0, 0, v2
	v_exp_f32_e32 v0, v0
	v_add_f32_e32 v170, v170, v2
	v_sub_f32_e32 v160, v160, v2
	v_sub_f32_e32 v161, v161, v2
	v_sub_f32_e32 v162, v162, v2
	v_sub_f32_e32 v163, v163, v2
	v_sub_f32_e32 v164, v164, v2
	v_sub_f32_e32 v165, v165, v2
	v_sub_f32_e32 v166, v166, v2
	v_sub_f32_e32 v167, v167, v2
	v_sub_f32_e32 v152, v152, v2
	v_sub_f32_e32 v153, v153, v2
	v_sub_f32_e32 v154, v154, v2
	v_sub_f32_e32 v155, v155, v2
	v_sub_f32_e32 v156, v156, v2
	v_sub_f32_e32 v157, v157, v2
	v_sub_f32_e32 v158, v158, v2
	v_sub_f32_e32 v159, v159, v2
	v_mul_f32_e32 v36, v36, v0
	v_pk_mul_f32 v[54:55], v[54:55], v[0:1] op_sel_hi:[1,0]
	v_pk_mul_f32 v[52:53], v[52:53], v[0:1] op_sel_hi:[1,0]
	v_pk_mul_f32 v[50:51], v[50:51], v[0:1] op_sel_hi:[1,0]
	v_pk_mul_f32 v[48:49], v[48:49], v[0:1] op_sel_hi:[1,0]
	v_pk_mul_f32 v[46:47], v[46:47], v[0:1] op_sel_hi:[1,0]
	v_pk_mul_f32 v[44:45], v[44:45], v[0:1] op_sel_hi:[1,0]
	v_pk_mul_f32 v[42:43], v[42:43], v[0:1] op_sel_hi:[1,0]
	v_pk_mul_f32 v[40:41], v[40:41], v[0:1] op_sel_hi:[1,0]
; __device__ __forceinline__ bf16x8 pack8(const f4& a, const f4& b) { return __builtin_bit_cast(bf16x8, pack8u(a, b)); }
; __device__ __forceinline__ float fexp2(float x) { return __builtin_amdgcn_exp2f(x); }
; #define MFMA16(a, b, c) __builtin_amdgcn_mfma_f32_16x16x32_bf16((a), (b), (c), 0, 0, 0)
;     ...
;     for (int ch = 0; ch < 2; ++ch)
; #pragma unroll
;         for (int kt = 0; kt < 2; ++kt) { f4 t = (f4){colbias, colbias, colbias, colbias}; t = MFMA16(kf[ch][kt][0], bq[0], t); s[ch][kt] = MFMA16(kf[ch][kt][1], bq[1], t); }
;     float mx = -1e30f;
; #pragma unroll
;     for (int ch = 0; ch < 2; ++ch)
; #pragma unroll
;         for (int h = 0; h < 2; ++h) mx = fmaxf(mx, fmaxf(fmaxf(s[ch][h][0], s[ch][h][1]), fmaxf(s[ch][h][2], s[ch][h][3])));
;     if (__any(mx > a.m + MAX_SLACK)) {
;         mx = fmaxf(mx, __shfl_xor(mx, 16)); mx = fmaxf(mx, __shfl_xor(mx, 32));
;         const float mn = fmaxf(a.m, mx), alpha = fexp2(a.m - mn); a.m = mn; a.l *= alpha;
; #pragma unroll
;         for (int c = 0; c < 4; ++c) a.o[c] = a.o[c] * alpha;
;     }
;     float ps = 0.f; bf16x8 pb[2];
; #pragma unroll
;     for (int ch = 0; ch < 2; ++ch) { f4 p0, p1;
; #pragma unroll
;         for (int j = 0; j < 4; ++j) { p0[j] = fexp2(s[ch][0][j] - a.m); p1[j] = fexp2(s[ch][1][j] - a.m); ps += p0[j] + p1[j]; }
;         pb[ch] = pack8(p0, p1); }
;     a.l += ps;
; #pragma unroll
;     for (int ch = 0; ch < 2; ++ch)
; #pragma unroll
;         for (int c = 0; c < 4; ++c) a.o[c] = MFMA16(vf[ch][c], pb[ch], a.o[c]);
.LBB0_1221:
	v_exp_f32_e32 v2, v160
	v_exp_f32_e32 v172, v164
	v_exp_f32_e32 v160, v161
	v_exp_f32_e32 v0, v165
	v_add_f32_e32 v161, v2, v172
	v_pk_add_f32 v[164:165], v[160:161], v[0:1]
	v_pk_add_f32 v[164:165], v[164:165], v[164:165] op_sel_hi:[0,1]
	v_exp_f32_e32 v161, v162
	v_exp_f32_e32 v173, v166
	v_exp_f32_e32 v162, v163
	v_exp_f32_e32 v164, v167
	v_add_f32_e32 v163, v161, v173
	v_cvt_pk_bf16_f32 v160, v2, v160
	v_pk_add_f32 v[166:167], v[162:163], v[164:165]
	v_pk_add_f32 v[166:167], v[166:167], v[166:167] op_sel_hi:[0,1]
	v_exp_f32_e32 v2, v152
	v_exp_f32_e32 v165, v156
	v_exp_f32_e32 v152, v153
	v_exp_f32_e32 v166, v157
	v_add_f32_e32 v153, v2, v165
	v_cvt_pk_bf16_f32 v161, v161, v162
	v_cvt_pk_bf16_f32 v162, v172, v0
	v_pk_add_f32 v[156:157], v[152:153], v[166:167]
	v_cvt_pk_bf16_f32 v163, v173, v164
	v_exp_f32_e32 v164, v158
	v_pk_add_f32 v[156:157], v[156:157], v[156:157] op_sel_hi:[0,1]
	v_mfma_f32_16x16x32_bf16 v[52:55], v[116:119], v[160:163], v[52:55]
	v_exp_f32_e32 v0, v154
	v_exp_f32_e32 v158, v155
	v_mfma_f32_16x16x32_bf16 v[48:51], v[112:115], v[160:163], v[48:51]
	v_exp_f32_e32 v156, v159
	v_cvt_pk_bf16_f32 v152, v2, v152
	v_cvt_pk_bf16_f32 v153, v0, v158
	v_mfma_f32_16x16x32_bf16 v[44:47], v[108:111], v[160:163], v[44:47]
	v_cvt_pk_bf16_f32 v154, v165, v166
	v_cvt_pk_bf16_f32 v155, v164, v156
	v_add_f32_e32 v159, v0, v164
	v_mfma_f32_16x16x32_bf16 v[40:43], v[104:107], v[160:163], v[40:43]
	v_add_f32_e64 v156, v158, v156
	v_add_f32_e64 v157, v159, v157
	v_add_f32_e32 v0, v156, v157
	v_mfma_f32_16x16x32_bf16 v[52:55], v[96:99], v[152:155], v[52:55]
	v_add_f32_e32 v36, v36, v0
	v_mfma_f32_16x16x32_bf16 v[48:51], v[100:103], v[152:155], v[48:51]
	v_mfma_f32_16x16x32_bf16 v[44:47], v[92:95], v[152:155], v[44:47]
	v_mfma_f32_16x16x32_bf16 v[40:43], v[88:91], v[152:155], v[40:43]
.LBB0_1222:
	s_andn2_b64 vcc, exec, s[22:23]
	s_cbranch_vccnz .LBB0_1212
	s_waitcnt lgkmcnt(0)
	v_lshrrev_b32_e32 v0, s40, v3
	v_and_b32_e32 v0, 1, v0
	v_cmp_eq_u32_e32 vcc, 1, v0
	s_nop 1
	v_cndmask_b32_e64 v152, v231, 0, vcc
	v_sub_f32_e32 v152, v152, v169
	v_mov_b32_e32 v153, v152
	v_mov_b32_e32 v154, v152
	v_mov_b32_e32 v155, v152
	s_nop 1
	v_mfma_f32_16x16x32_bf16 v[140:143], v[140:143], v[12:15], v[152:155]
	v_mfma_f32_16x16x32_bf16 v[144:147], v[144:147], v[12:15], v[152:155]
	v_mfma_f32_16x16x32_bf16 v[140:143], v[148:151], v[16:19], v[140:143]
	v_mfma_f32_16x16x32_bf16 v[144:147], v[128:131], v[16:19], v[144:147]
	v_mfma_f32_16x16x32_bf16 v[128:131], v[136:139], v[12:15], v[152:155]
	s_nop 5
	v_max_f32_e32 v0, v143, v143
	v_max_f32_e32 v2, v142, v142
	v_max_f32_e32 v0, v2, v0
	v_mfma_f32_16x16x32_bf16 v[124:127], v[124:127], v[12:15], v[152:155]
	v_max_f32_e32 v2, v147, v147
	v_max_f32_e32 v3, v146, v146
	v_max_f32_e32 v2, v3, v2
	v_mfma_f32_16x16x32_bf16 v[128:131], v[132:135], v[16:19], v[128:131]
	v_max3_f32 v0, v140, v141, v0
	v_max3_f32 v2, v144, v145, v2
	v_max3_f32 v0, v0, s93, v2
	v_mfma_f32_16x16x32_bf16 v[120:123], v[120:123], v[16:19], v[124:127]
	s_nop 3
	v_max_f32_e32 v2, v131, v131
	v_max_f32_e32 v3, v130, v130
	v_max_f32_e32 v2, v3, v2
	s_nop 0
	v_max_f32_e32 v3, v123, v123
	v_max_f32_e32 v124, v122, v122
	v_max_f32_e32 v3, v124, v3
	v_max3_f32 v2, v128, v129, v2
	v_max3_f32 v3, v120, v121, v3
	v_max3_f32 v0, v0, v2, v3
	v_cmp_lt_f32_e32 vcc, 0x41000000, v0
	s_cbranch_vccz .LBB0_1211
	ds_bpermute_b32 v2, v217, v0
	v_max_f32_e32 v0, v0, v0
	s_waitcnt lgkmcnt(0)
	v_max_f32_e32 v2, v2, v2
	v_max_f32_e32 v0, v0, v2
	ds_bpermute_b32 v2, v219, v0
	s_waitcnt lgkmcnt(0)
	v_max3_f32 v2, 0, v0, v2
	v_sub_f32_e32 v0, 0, v2
	v_exp_f32_e32 v0, v0
	v_add_f32_e32 v169, v169, v2
	v_sub_f32_e32 v140, v140, v2
	v_sub_f32_e32 v141, v141, v2
	v_sub_f32_e32 v142, v142, v2
	v_sub_f32_e32 v143, v143, v2
	v_sub_f32_e32 v144, v144, v2
	v_sub_f32_e32 v145, v145, v2
	v_sub_f32_e32 v146, v146, v2
	v_sub_f32_e32 v147, v147, v2
	v_sub_f32_e32 v128, v128, v2
	v_sub_f32_e32 v129, v129, v2
	v_sub_f32_e32 v130, v130, v2
	v_sub_f32_e32 v131, v131, v2
	v_sub_f32_e32 v120, v120, v2
	v_sub_f32_e32 v121, v121, v2
	v_sub_f32_e32 v122, v122, v2
	v_sub_f32_e32 v123, v123, v2
	v_mul_f32_e32 v168, v168, v0
	v_pk_mul_f32 v[34:35], v[34:35], v[0:1] op_sel_hi:[1,0]
	v_pk_mul_f32 v[32:33], v[32:33], v[0:1] op_sel_hi:[1,0]
	v_pk_mul_f32 v[30:31], v[30:31], v[0:1] op_sel_hi:[1,0]
	v_pk_mul_f32 v[28:29], v[28:29], v[0:1] op_sel_hi:[1,0]
	v_pk_mul_f32 v[26:27], v[26:27], v[0:1] op_sel_hi:[1,0]
	v_pk_mul_f32 v[24:25], v[24:25], v[0:1] op_sel_hi:[1,0]
	v_pk_mul_f32 v[22:23], v[22:23], v[0:1] op_sel_hi:[1,0]
	v_pk_mul_f32 v[20:21], v[20:21], v[0:1] op_sel_hi:[1,0]
	s_branch .LBB0_1211

; #pragma unroll
;     for (int c = 0; c < 4; ++c) a.o[c] = (f4){0.f, 0.f, 0.f, 0.f}; }
; __device__ __forceinline__ void nsa_block_task(Ctx& C, int task, bf16* ONSA_OUT) {
;     ...
;         AttnAcc a[2]; attn_init(a[0]); attn_init(a[1]);
.LBB0_1229:
	v_mov_b32_e32 v36, 0
	v_mov_b32_e32 v37, v36
	v_mov_b32_e32 v38, v36
	v_mov_b32_e32 v39, v36
	v_mov_b64_e32 v[54:55], v[38:39]
	v_mov_b64_e32 v[50:51], v[38:39]
	v_mov_b64_e32 v[46:47], v[38:39]
	v_mov_b64_e32 v[42:43], v[38:39]
	v_mov_b64_e32 v[32:33], v[36:37]
	v_mov_b64_e32 v[28:29], v[36:37]
	v_mov_b64_e32 v[24:25], v[36:37]
	v_mov_b64_e32 v[20:21], v[36:37]
	v_mov_b32_e32 v170, 0xc4800000
	v_mov_b64_e32 v[52:53], v[36:37]
	v_mov_b64_e32 v[48:49], v[36:37]
	v_mov_b64_e32 v[44:45], v[36:37]
	v_mov_b64_e32 v[40:41], v[36:37]
	v_mov_b32_e32 v169, 0xc4800000
	v_mov_b32_e32 v168, v36
	v_mov_b64_e32 v[34:35], v[38:39]
	v_mov_b64_e32 v[30:31], v[38:39]
	v_mov_b64_e32 v[26:27], v[38:39]
	v_mov_b64_e32 v[22:23], v[38:39]

; __global__ void __launch_bounds__(NWAVES * 64, 2) hybrid_fwd(Args args) {
	.amdhsa_kernel _Z10hybrid_fwd4Args
		.amdhsa_group_segment_fixed_size 0
		.amdhsa_private_segment_fixed_size 0
		.amdhsa_kernarg_size 472
		.amdhsa_user_sgpr_count 2
		.amdhsa_user_sgpr_dispatch_ptr 0
		.amdhsa_user_sgpr_queue_ptr 0
		.amdhsa_user_sgpr_kernarg_segment_ptr 1
		.amdhsa_user_sgpr_dispatch_id 0
		.amdhsa_user_sgpr_kernarg_preload_length 0
		.amdhsa_user_sgpr_kernarg_preload_offset 0
		.amdhsa_user_sgpr_private_segment_size 0
		.amdhsa_uses_dynamic_stack 0
		.amdhsa_enable_private_segment 0
		.amdhsa_system_sgpr_workgroup_id_x 1
		.amdhsa_system_sgpr_workgroup_id_y 0
		.amdhsa_system_sgpr_workgroup_id_z 0
		.amdhsa_system_sgpr_workgroup_info 0
		.amdhsa_system_vgpr_workitem_id 0
		.amdhsa_next_free_vgpr 256
		.amdhsa_next_free_sgpr 102
		.amdhsa_accum_offset 256
		.amdhsa_reserve_vcc 1
		.amdhsa_float_round_mode_32 0
		.amdhsa_float_round_mode_16_64 0
		.amdhsa_float_denorm_mode_32 3
		.amdhsa_float_denorm_mode_16_64 3
		.amdhsa_dx10_clamp 1
		.amdhsa_ieee_mode 1
		.amdhsa_fp16_overflow 0
		.amdhsa_tg_split 0
		.amdhsa_exception_fp_ieee_invalid_op 0
		.amdhsa_exception_fp_denorm_src 0
		.amdhsa_exception_fp_ieee_div_zero 0
		.amdhsa_exception_fp_ieee_overflow 0
		.amdhsa_exception_fp_ieee_underflow 0
		.amdhsa_exception_fp_ieee_inexact 0
		.amdhsa_exception_int_div_zero 0
	.end_amdhsa_kernel

; __global__ void __launch_bounds__(NWAVES * 64, 2) hybrid_fwd(Args args) {
amdhsa.kernels:
  - .agpr_count:     0
    .args:
      - .offset:         0
        .size:           216
        .value_kind:     by_value
      - .offset:         216
        .size:           4
        .value_kind:     hidden_block_count_x
      - .offset:         220
        .size:           4
        .value_kind:     hidden_block_count_y
      - .offset:         224
        .size:           4
        .value_kind:     hidden_block_count_z
      - .offset:         228
        .size:           2
        .value_kind:     hidden_group_size_x
      - .offset:         230
        .size:           2
        .value_kind:     hidden_group_size_y
      - .offset:         232
        .size:           2
        .value_kind:     hidden_group_size_z
      - .offset:         234
        .size:           2
        .value_kind:     hidden_remainder_x
      - .offset:         236
        .size:           2
        .value_kind:     hidden_remainder_y
      - .offset:         238
        .size:           2
        .value_kind:     hidden_remainder_z
      - .offset:         256
        .size:           8
        .value_kind:     hidden_global_offset_x
      - .offset:         264
        .size:           8
        .value_kind:     hidden_global_offset_y
      - .offset:         272
        .size:           8
        .value_kind:     hidden_global_offset_z
      - .offset:         280
        .size:           2
        .value_kind:     hidden_grid_dims
      - .offset:         336
        .size:           4
        .value_kind:     hidden_dynamic_lds_size
    .group_segment_fixed_size: 0
    .kernarg_segment_align: 8
    .kernarg_segment_size: 472
    .language:       OpenCL C
    .language_version:
      - 2
      - 0
    .max_flat_workgroup_size: 512
    .name:           _Z10hybrid_fwd4Args
    .private_segment_fixed_size: 0
    .sgpr_count:     108
    .sgpr_spill_count: 58
    .symbol:         _Z10hybrid_fwd4Args.kd
    .uniform_work_group_size: 1
    .uses_dynamic_stack: false
    .vgpr_count:     256
    .vgpr_spill_count: 0
    .wavefront_size: 64
